# K=1024 GEMM loops fully unrolled with 3-deep register prefetch ring; attention-first draw order in phase 6
# speedup vs baseline: 1.0743x; 1.0113x over previous
; template <class Epi, class ColV>
; DI void gemm_tile(const bf16_t* __restrict__ A, int lda, const bf16_t* __restrict__ Bt, int ldb, int K, int m0, int n0, unsigned char* smem, Epi epi, ColV colv, const bf16_t* __restrict__ HYT = nullptr) {
;     ...
;     auto step = [&](int kt, u32x4 (&ldset)[8], const u32x4 (&stset)[8]) {
;         const int buf = kt & 1;
;         if (kt + 2 < nk) gload(ldset, kt + 2);
;         const bf16_t* Ab = As + (buf * 128 + 64 * wr + li) * LS + 8 * lh;
;         const bf16_t* Bb = Bs + (buf * 128 + 64 * wc + li) * LS + 8 * lh;
;         bf16x8 fa[2][2], fb[2][2], ga[2][2], gb[2][2];
; #pragma unroll
;         for (int k2 = 0; k2 < 2; ++k2) { fa[k2][0] = ld8(Ab + 16 * k2); fa[k2][1] = ld8(Ab + 32 * LS + 16 * k2); fb[k2][0] = ld8(Bb + 16 * k2); fb[k2][1] = ld8(Bb + 32 * LS + 16 * k2); }
;         __builtin_amdgcn_sched_barrier(0);
; #pragma unroll
;         for (int k2 = 0; k2 < 2; ++k2) {
;             acc[0][0] = MFMA(fa[k2][0], fb[k2][0], acc[0][0]); acc[0][1] = MFMA(fa[k2][0], fb[k2][1], acc[0][1]);
;             acc[1][0] = MFMA(fa[k2][1], fb[k2][0], acc[1][0]); acc[1][1] = MFMA(fa[k2][1], fb[k2][1], acc[1][1]);
;         }
; #pragma unroll
;         for (int k2 = 0; k2 < 2; ++k2) { const int ks = 2 + k2; ga[k2][0] = ld8(Ab + 16 * ks); ga[k2][1] = ld8(Ab + 32 * LS + 16 * ks); gb[k2][0] = ld8(Bb + 16 * ks); gb[k2][1] = ld8(Bb + 32 * LS + 16 * ks); }
; #pragma unroll
;         for (int k2 = 0; k2 < 2; ++k2) {
;             acc[0][0] = MFMA(ga[k2][0], gb[k2][0], acc[0][0]); acc[0][1] = MFMA(ga[k2][0], gb[k2][1], acc[0][1]);
;             acc[1][0] = MFMA(ga[k2][1], gb[k2][0], acc[1][0]); acc[1][1] = MFMA(ga[k2][1], gb[k2][1], acc[1][1]);
;         }
;         if (kt + 1 < nk) sstore(stset, buf ^ 1, kt + 1);
; #pragma unroll
;         for (int i = 0; i < 8; ++i) { __builtin_amdgcn_sched_group_barrier(0x008, 1, 0); __builtin_amdgcn_sched_group_barrier(0x100, 1, 0); }
; #pragma unroll
;         for (int i = 0; i < 8; ++i) { __builtin_amdgcn_sched_group_barrier(0x008, 1, 0); __builtin_amdgcn_sched_group_barrier(0x200, 1, 0); }
;         __builtin_amdgcn_sched_barrier(0);
;         __syncthreads();
;     };
;     gload(R0, 0); gload(R1, 1);
;     sstore(R0, 0, 0); __syncthreads();
;     for (int kt = 0; kt < nk; kt += 2) {
;         step(kt, R0, R1);
;         if (kt + 1 < nk) step(kt + 1, R1, R0);
;     }
.LBB0_56:
	s_cmp_lt_u32 s40, 14
	s_cselect_b64 s[18:19], -1, 0
	s_cmp_gt_u32 s40, 13
	s_cselect_b64 s[12:13], -1, 0
	s_and_b64 vcc, exec, s[12:13]
	v_lshl_add_u64 v[164:165], v[144:145], 0, v[2:3]
	v_lshl_add_u64 v[162:163], v[142:143], 0, v[2:3]
	v_lshl_add_u64 v[160:161], v[140:141], 0, v[2:3]
	v_lshl_add_u64 v[158:159], v[138:139], 0, v[2:3]
	v_lshl_add_u64 v[156:157], v[136:137], 0, v[2:3]
	v_lshl_add_u64 v[154:155], v[134:135], 0, v[2:3]
	v_lshl_add_u64 v[152:153], v[132:133], 0, v[2:3]
	v_lshl_add_u64 v[146:147], v[0:1], 0, v[2:3]
	s_mov_b32 s100, 0x26ca000
	s_mov_b32 s101, 0
	v_lshl_add_u64 v[164:165], v[164:165], 0, s[100:101]
	v_lshl_add_u64 v[160:161], v[160:161], 0, s[100:101]
	v_lshl_add_u64 v[156:157], v[156:157], 0, s[100:101]
	v_lshl_add_u64 v[152:153], v[152:153], 0, s[100:101]
	s_mov_b32 s100, 0x680000
	s_mov_b32 s101, 0
	v_lshl_add_u64 v[162:163], v[162:163], 0, s[100:101]
	v_lshl_add_u64 v[158:159], v[158:159], 0, s[100:101]
	v_lshl_add_u64 v[154:155], v[154:155], 0, s[100:101]
	v_lshl_add_u64 v[146:147], v[146:147], 0, s[100:101]
	global_load_dwordx4 v[132:135], v[164:165], off offset:256
	global_load_dwordx4 v[136:139], v[162:163], off offset:256
	global_load_dwordx4 v[140:143], v[160:161], off offset:256
	global_load_dwordx4 v[198:201], v[158:159], off offset:256
	global_load_dwordx4 v[226:229], v[156:157], off offset:256
	global_load_dwordx4 v[230:233], v[154:155], off offset:256
	global_load_dwordx4 v[242:245], v[152:153], off offset:256
	global_load_dwordx4 v[246:249], v[146:147], off offset:256
	global_load_dwordx4 v[68:71], v[164:165], off offset:384
	global_load_dwordx4 v[72:75], v[162:163], off offset:384
	global_load_dwordx4 v[76:79], v[160:161], off offset:384
	global_load_dwordx4 v[80:83], v[158:159], off offset:384
	global_load_dwordx4 v[84:87], v[156:157], off offset:384
	global_load_dwordx4 v[92:95], v[154:155], off offset:384
	global_load_dwordx4 v[104:107], v[152:153], off offset:384
	global_load_dwordx4 v[112:115], v[146:147], off offset:384
	ds_read_b128 v[174:177], v194
	ds_read_b128 v[178:181], v194 offset:32
	ds_read_b128 v[202:205], v194 offset:4608
	ds_read_b128 v[206:209], v194 offset:4640
	ds_read_b128 v[210:213], v195 offset:36864
	ds_read_b128 v[214:217], v195 offset:36896
	ds_read_b128 v[218:221], v195 offset:41472
	ds_read_b128 v[222:225], v195 offset:41504
	s_waitcnt lgkmcnt(3)
	v_mfma_f32_32x32x16_bf16 v[52:67], v[174:177], v[210:213], v[52:67]
	s_waitcnt lgkmcnt(1)
	v_mfma_f32_32x32x16_bf16 v[36:51], v[174:177], v[218:221], v[36:51]
	v_mfma_f32_32x32x16_bf16 v[4:19], v[202:205], v[218:221], v[4:19]
	s_waitcnt lgkmcnt(0)
	v_mfma_f32_32x32x16_bf16 v[36:51], v[178:181], v[222:225], v[36:51]
	v_mfma_f32_32x32x16_bf16 v[4:19], v[206:209], v[222:225], v[4:19]
	ds_read_b128 v[222:225], v195 offset:41568
	ds_read_b128 v[174:177], v194 offset:4672
	v_mfma_f32_32x32x16_bf16 v[20:35], v[202:205], v[210:213], v[20:35]
	ds_read_b128 v[210:213], v194 offset:4704
	ds_read_b128 v[202:205], v194 offset:64
	v_mfma_f32_32x32x16_bf16 v[52:67], v[178:181], v[214:217], v[52:67]
	ds_read_b128 v[218:221], v195 offset:36960
	ds_read_b128 v[178:181], v195 offset:41536
	v_mfma_f32_32x32x16_bf16 v[20:35], v[206:209], v[214:217], v[20:35]
	ds_read_b128 v[214:217], v195 offset:36928
	ds_read_b128 v[206:209], v194 offset:96
	s_waitcnt lgkmcnt(1)
	v_mfma_f32_32x32x16_bf16 v[52:67], v[202:205], v[214:217], v[52:67]
	s_waitcnt vmcnt(16)
	ds_write_b128 v167, v[88:91] offset:18432
	v_mfma_f32_32x32x16_bf16 v[36:51], v[202:205], v[178:181], v[36:51]
	ds_write_b128 v167, v[96:99] offset:55296
	v_mfma_f32_32x32x16_bf16 v[20:35], v[174:177], v[214:217], v[20:35]
	ds_write_b128 v190, v[100:103] offset:18432
	v_mfma_f32_32x32x16_bf16 v[4:19], v[174:177], v[178:181], v[4:19]
	ds_write_b128 v190, v[108:111] offset:55296
	s_waitcnt lgkmcnt(4)
	v_mfma_f32_32x32x16_bf16 v[52:67], v[206:209], v[218:221], v[52:67]
	ds_write_b128 v191, v[116:119] offset:18432
	v_mfma_f32_32x32x16_bf16 v[36:51], v[206:209], v[222:225], v[36:51]
	ds_write_b128 v191, v[120:123] offset:55296
	v_mfma_f32_32x32x16_bf16 v[20:35], v[210:213], v[218:221], v[20:35]
	ds_write_b128 v192, v[124:127] offset:18432
	v_mfma_f32_32x32x16_bf16 v[4:19], v[210:213], v[222:225], v[4:19]
	ds_write_b128 v192, v[128:131] offset:55296
	s_waitcnt lgkmcnt(0)
	s_barrier
; #define MFMA(a, b, c) __builtin_amdgcn_mfma_f32_32x32x16_bf16((a), (b), (c), 0, 0, 0)
; template <class Epi, class ColV>
; DI void gemm_tile(const bf16_t* __restrict__ A, int lda, const bf16_t* __restrict__ Bt, int ldb, int K, int m0, int n0, unsigned char* smem, Epi epi, ColV colv, const bf16_t* __restrict__ HYT = nullptr) {
;     ...
;     auto step = [&](int kt, u32x4 (&ldset)[8], const u32x4 (&stset)[8]) {
;         const int buf = kt & 1;
;         if (kt + 2 < nk) gload(ldset, kt + 2);
;         const bf16_t* Ab = As + (buf * 128 + 64 * wr + li) * LS + 8 * lh;
;         const bf16_t* Bb = Bs + (buf * 128 + 64 * wc + li) * LS + 8 * lh;
;         bf16x8 fa[2][2], fb[2][2], ga[2][2], gb[2][2];
; #pragma unroll
;         for (int k2 = 0; k2 < 2; ++k2) { fa[k2][0] = ld8(Ab + 16 * k2); fa[k2][1] = ld8(Ab + 32 * LS + 16 * k2); fb[k2][0] = ld8(Bb + 16 * k2); fb[k2][1] = ld8(Bb + 32 * LS + 16 * k2); }
;         __builtin_amdgcn_sched_barrier(0);
; #pragma unroll
;         for (int k2 = 0; k2 < 2; ++k2) {
;             acc[0][0] = MFMA(fa[k2][0], fb[k2][0], acc[0][0]); acc[0][1] = MFMA(fa[k2][0], fb[k2][1], acc[0][1]);
;             acc[1][0] = MFMA(fa[k2][1], fb[k2][0], acc[1][0]); acc[1][1] = MFMA(fa[k2][1], fb[k2][1], acc[1][1]);
;         }
; #pragma unroll
;         for (int k2 = 0; k2 < 2; ++k2) { const int ks = 2 + k2; ga[k2][0] = ld8(Ab + 16 * ks); ga[k2][1] = ld8(Ab + 32 * LS + 16 * ks); gb[k2][0] = ld8(Bb + 16 * ks); gb[k2][1] = ld8(Bb + 32 * LS + 16 * ks); }
; #pragma unroll
;         for (int k2 = 0; k2 < 2; ++k2) {
;             acc[0][0] = MFMA(ga[k2][0], gb[k2][0], acc[0][0]); acc[0][1] = MFMA(ga[k2][0], gb[k2][1], acc[0][1]);
;             acc[1][0] = MFMA(ga[k2][1], gb[k2][0], acc[1][0]); acc[1][1] = MFMA(ga[k2][1], gb[k2][1], acc[1][1]);
;         }
;         if (kt + 1 < nk) sstore(stset, buf ^ 1, kt + 1);
; #pragma unroll
;         for (int i = 0; i < 8; ++i) { __builtin_amdgcn_sched_group_barrier(0x008, 1, 0); __builtin_amdgcn_sched_group_barrier(0x100, 1, 0); }
; #pragma unroll
;         for (int i = 0; i < 8; ++i) { __builtin_amdgcn_sched_group_barrier(0x008, 1, 0); __builtin_amdgcn_sched_group_barrier(0x200, 1, 0); }
;         __builtin_amdgcn_sched_barrier(0);
;         __syncthreads();
	global_load_dwordx4 v[88:91], v[164:165], off offset:512
	global_load_dwordx4 v[96:99], v[162:163], off offset:512
	global_load_dwordx4 v[100:103], v[160:161], off offset:512
	global_load_dwordx4 v[108:111], v[158:159], off offset:512
	global_load_dwordx4 v[116:119], v[156:157], off offset:512
	global_load_dwordx4 v[120:123], v[154:155], off offset:512
	global_load_dwordx4 v[124:127], v[152:153], off offset:512
	global_load_dwordx4 v[128:131], v[146:147], off offset:512
	ds_read_b128 v[174:177], v196
	ds_read_b128 v[178:181], v196 offset:32
	ds_read_b128 v[202:205], v196 offset:4608
	ds_read_b128 v[206:209], v196 offset:4640
	ds_read_b128 v[210:213], v197 offset:36864
	ds_read_b128 v[214:217], v197 offset:36896
	ds_read_b128 v[218:221], v197 offset:41472
	ds_read_b128 v[222:225], v197 offset:41504
	s_waitcnt lgkmcnt(3)
	v_mfma_f32_32x32x16_bf16 v[52:67], v[174:177], v[210:213], v[52:67]
	s_waitcnt lgkmcnt(1)
	v_mfma_f32_32x32x16_bf16 v[36:51], v[174:177], v[218:221], v[36:51]
	v_mfma_f32_32x32x16_bf16 v[4:19], v[202:205], v[218:221], v[4:19]
	s_waitcnt lgkmcnt(0)
	v_mfma_f32_32x32x16_bf16 v[36:51], v[178:181], v[222:225], v[36:51]
	v_mfma_f32_32x32x16_bf16 v[4:19], v[206:209], v[222:225], v[4:19]
	ds_read_b128 v[222:225], v197 offset:41568
	ds_read_b128 v[174:177], v196 offset:4672
	v_mfma_f32_32x32x16_bf16 v[20:35], v[202:205], v[210:213], v[20:35]
	ds_read_b128 v[210:213], v196 offset:4704
	ds_read_b128 v[202:205], v196 offset:64
	v_mfma_f32_32x32x16_bf16 v[52:67], v[178:181], v[214:217], v[52:67]
	ds_read_b128 v[218:221], v197 offset:36960
	ds_read_b128 v[178:181], v197 offset:41536
	v_mfma_f32_32x32x16_bf16 v[20:35], v[206:209], v[214:217], v[20:35]
	ds_read_b128 v[214:217], v197 offset:36928
	ds_read_b128 v[206:209], v196 offset:96
	s_waitcnt lgkmcnt(1)
	v_mfma_f32_32x32x16_bf16 v[52:67], v[202:205], v[214:217], v[52:67]
	s_waitcnt vmcnt(23)
	ds_write_b128 v167, v[132:135]
	v_mfma_f32_32x32x16_bf16 v[36:51], v[202:205], v[178:181], v[36:51]
	s_waitcnt vmcnt(22)
	ds_write_b128 v167, v[136:139] offset:36864
	v_mfma_f32_32x32x16_bf16 v[20:35], v[174:177], v[214:217], v[20:35]
	s_waitcnt vmcnt(21)
	ds_write_b128 v190, v[140:143]
	v_mfma_f32_32x32x16_bf16 v[4:19], v[174:177], v[178:181], v[4:19]
	s_waitcnt vmcnt(20)
	ds_write_b128 v190, v[198:201] offset:36864
	s_waitcnt lgkmcnt(4)
	v_mfma_f32_32x32x16_bf16 v[52:67], v[206:209], v[218:221], v[52:67]
	s_waitcnt vmcnt(19)
	ds_write_b128 v191, v[226:229]
	v_mfma_f32_32x32x16_bf16 v[36:51], v[206:209], v[222:225], v[36:51]
	s_waitcnt vmcnt(18)
	ds_write_b128 v191, v[230:233] offset:36864
	v_mfma_f32_32x32x16_bf16 v[20:35], v[210:213], v[218:221], v[20:35]
	s_waitcnt vmcnt(17)
	ds_write_b128 v192, v[242:245]
	v_mfma_f32_32x32x16_bf16 v[4:19], v[210:213], v[222:225], v[4:19]
	s_waitcnt vmcnt(16)
	ds_write_b128 v192, v[246:249] offset:36864
	s_waitcnt lgkmcnt(0)
	s_barrier
	global_load_dwordx4 v[132:135], v[164:165], off offset:640
	global_load_dwordx4 v[136:139], v[162:163], off offset:640
	global_load_dwordx4 v[140:143], v[160:161], off offset:640
	global_load_dwordx4 v[198:201], v[158:159], off offset:640
	global_load_dwordx4 v[226:229], v[156:157], off offset:640
	global_load_dwordx4 v[230:233], v[154:155], off offset:640
	global_load_dwordx4 v[242:245], v[152:153], off offset:640
	global_load_dwordx4 v[246:249], v[146:147], off offset:640
	ds_read_b128 v[174:177], v194
	ds_read_b128 v[178:181], v194 offset:32
	ds_read_b128 v[202:205], v194 offset:4608
	ds_read_b128 v[206:209], v194 offset:4640
	ds_read_b128 v[210:213], v195 offset:36864
	ds_read_b128 v[214:217], v195 offset:36896
	ds_read_b128 v[218:221], v195 offset:41472
	ds_read_b128 v[222:225], v195 offset:41504
	s_waitcnt lgkmcnt(3)
	v_mfma_f32_32x32x16_bf16 v[52:67], v[174:177], v[210:213], v[52:67]
	s_waitcnt lgkmcnt(1)
	v_mfma_f32_32x32x16_bf16 v[36:51], v[174:177], v[218:221], v[36:51]
	v_mfma_f32_32x32x16_bf16 v[4:19], v[202:205], v[218:221], v[4:19]
	s_waitcnt lgkmcnt(0)
	v_mfma_f32_32x32x16_bf16 v[36:51], v[178:181], v[222:225], v[36:51]
	v_mfma_f32_32x32x16_bf16 v[4:19], v[206:209], v[222:225], v[4:19]
	ds_read_b128 v[222:225], v195 offset:41568
	ds_read_b128 v[174:177], v194 offset:4672
	v_mfma_f32_32x32x16_bf16 v[20:35], v[202:205], v[210:213], v[20:35]
	ds_read_b128 v[210:213], v194 offset:4704
	ds_read_b128 v[202:205], v194 offset:64
	v_mfma_f32_32x32x16_bf16 v[52:67], v[178:181], v[214:217], v[52:67]
	ds_read_b128 v[218:221], v195 offset:36960
	ds_read_b128 v[178:181], v195 offset:41536
	v_mfma_f32_32x32x16_bf16 v[20:35], v[206:209], v[214:217], v[20:35]
	ds_read_b128 v[214:217], v195 offset:36928
	ds_read_b128 v[206:209], v194 offset:96
	s_waitcnt lgkmcnt(1)
	v_mfma_f32_32x32x16_bf16 v[52:67], v[202:205], v[214:217], v[52:67]
	s_waitcnt vmcnt(23)
	ds_write_b128 v167, v[68:71] offset:18432
	v_mfma_f32_32x32x16_bf16 v[36:51], v[202:205], v[178:181], v[36:51]
	s_waitcnt vmcnt(22)
	ds_write_b128 v167, v[72:75] offset:55296
	v_mfma_f32_32x32x16_bf16 v[20:35], v[174:177], v[214:217], v[20:35]
	s_waitcnt vmcnt(21)
	ds_write_b128 v190, v[76:79] offset:18432
	v_mfma_f32_32x32x16_bf16 v[4:19], v[174:177], v[178:181], v[4:19]
	s_waitcnt vmcnt(20)
	ds_write_b128 v190, v[80:83] offset:55296
	s_waitcnt lgkmcnt(4)
	v_mfma_f32_32x32x16_bf16 v[52:67], v[206:209], v[218:221], v[52:67]
	s_waitcnt vmcnt(19)
	ds_write_b128 v191, v[84:87] offset:18432
	v_mfma_f32_32x32x16_bf16 v[36:51], v[206:209], v[222:225], v[36:51]
	s_waitcnt vmcnt(18)
	ds_write_b128 v191, v[92:95] offset:55296
	v_mfma_f32_32x32x16_bf16 v[20:35], v[210:213], v[218:221], v[20:35]
	s_waitcnt vmcnt(17)
	ds_write_b128 v192, v[104:107] offset:18432
	v_mfma_f32_32x32x16_bf16 v[4:19], v[210:213], v[222:225], v[4:19]
	s_waitcnt vmcnt(16)
	ds_write_b128 v192, v[112:115] offset:55296
	s_waitcnt lgkmcnt(0)
	s_barrier
; #define MFMA(a, b, c) __builtin_amdgcn_mfma_f32_32x32x16_bf16((a), (b), (c), 0, 0, 0)
; template <class Epi, class ColV>
; DI void gemm_tile(const bf16_t* __restrict__ A, int lda, const bf16_t* __restrict__ Bt, int ldb, int K, int m0, int n0, unsigned char* smem, Epi epi, ColV colv, const bf16_t* __restrict__ HYT = nullptr) {
;     ...
;     auto step = [&](int kt, u32x4 (&ldset)[8], const u32x4 (&stset)[8]) {
;         const int buf = kt & 1;
;         if (kt + 2 < nk) gload(ldset, kt + 2);
;         const bf16_t* Ab = As + (buf * 128 + 64 * wr + li) * LS + 8 * lh;
;         const bf16_t* Bb = Bs + (buf * 128 + 64 * wc + li) * LS + 8 * lh;
;         bf16x8 fa[2][2], fb[2][2], ga[2][2], gb[2][2];
; #pragma unroll
;         for (int k2 = 0; k2 < 2; ++k2) { fa[k2][0] = ld8(Ab + 16 * k2); fa[k2][1] = ld8(Ab + 32 * LS + 16 * k2); fb[k2][0] = ld8(Bb + 16 * k2); fb[k2][1] = ld8(Bb + 32 * LS + 16 * k2); }
;         __builtin_amdgcn_sched_barrier(0);
; #pragma unroll
;         for (int k2 = 0; k2 < 2; ++k2) {
;             acc[0][0] = MFMA(fa[k2][0], fb[k2][0], acc[0][0]); acc[0][1] = MFMA(fa[k2][0], fb[k2][1], acc[0][1]);
;             acc[1][0] = MFMA(fa[k2][1], fb[k2][0], acc[1][0]); acc[1][1] = MFMA(fa[k2][1], fb[k2][1], acc[1][1]);
;         }
; #pragma unroll
;         for (int k2 = 0; k2 < 2; ++k2) { const int ks = 2 + k2; ga[k2][0] = ld8(Ab + 16 * ks); ga[k2][1] = ld8(Ab + 32 * LS + 16 * ks); gb[k2][0] = ld8(Bb + 16 * ks); gb[k2][1] = ld8(Bb + 32 * LS + 16 * ks); }
; #pragma unroll
;         for (int k2 = 0; k2 < 2; ++k2) {
;             acc[0][0] = MFMA(ga[k2][0], gb[k2][0], acc[0][0]); acc[0][1] = MFMA(ga[k2][0], gb[k2][1], acc[0][1]);
;             acc[1][0] = MFMA(ga[k2][1], gb[k2][0], acc[1][0]); acc[1][1] = MFMA(ga[k2][1], gb[k2][1], acc[1][1]);
;         }
;         if (kt + 1 < nk) sstore(stset, buf ^ 1, kt + 1);
; #pragma unroll
;         for (int i = 0; i < 8; ++i) { __builtin_amdgcn_sched_group_barrier(0x008, 1, 0); __builtin_amdgcn_sched_group_barrier(0x100, 1, 0); }
; #pragma unroll
;         for (int i = 0; i < 8; ++i) { __builtin_amdgcn_sched_group_barrier(0x008, 1, 0); __builtin_amdgcn_sched_group_barrier(0x200, 1, 0); }
;         __builtin_amdgcn_sched_barrier(0);
;         __syncthreads();
	global_load_dwordx4 v[68:71], v[164:165], off offset:768
	global_load_dwordx4 v[72:75], v[162:163], off offset:768
	global_load_dwordx4 v[76:79], v[160:161], off offset:768
	global_load_dwordx4 v[80:83], v[158:159], off offset:768
	global_load_dwordx4 v[84:87], v[156:157], off offset:768
	global_load_dwordx4 v[92:95], v[154:155], off offset:768
	global_load_dwordx4 v[104:107], v[152:153], off offset:768
	global_load_dwordx4 v[112:115], v[146:147], off offset:768
	ds_read_b128 v[174:177], v196
	ds_read_b128 v[178:181], v196 offset:32
	ds_read_b128 v[202:205], v196 offset:4608
	ds_read_b128 v[206:209], v196 offset:4640
	ds_read_b128 v[210:213], v197 offset:36864
	ds_read_b128 v[214:217], v197 offset:36896
	ds_read_b128 v[218:221], v197 offset:41472
	ds_read_b128 v[222:225], v197 offset:41504
	s_waitcnt lgkmcnt(3)
	v_mfma_f32_32x32x16_bf16 v[52:67], v[174:177], v[210:213], v[52:67]
	s_waitcnt lgkmcnt(1)
	v_mfma_f32_32x32x16_bf16 v[36:51], v[174:177], v[218:221], v[36:51]
	v_mfma_f32_32x32x16_bf16 v[4:19], v[202:205], v[218:221], v[4:19]
	s_waitcnt lgkmcnt(0)
	v_mfma_f32_32x32x16_bf16 v[36:51], v[178:181], v[222:225], v[36:51]
	v_mfma_f32_32x32x16_bf16 v[4:19], v[206:209], v[222:225], v[4:19]
	ds_read_b128 v[222:225], v197 offset:41568
	ds_read_b128 v[174:177], v196 offset:4672
	v_mfma_f32_32x32x16_bf16 v[20:35], v[202:205], v[210:213], v[20:35]
	ds_read_b128 v[210:213], v196 offset:4704
	ds_read_b128 v[202:205], v196 offset:64
	v_mfma_f32_32x32x16_bf16 v[52:67], v[178:181], v[214:217], v[52:67]
	ds_read_b128 v[218:221], v197 offset:36960
	ds_read_b128 v[178:181], v197 offset:41536
	v_mfma_f32_32x32x16_bf16 v[20:35], v[206:209], v[214:217], v[20:35]
	ds_read_b128 v[214:217], v197 offset:36928
	ds_read_b128 v[206:209], v196 offset:96
	s_waitcnt lgkmcnt(1)
	v_mfma_f32_32x32x16_bf16 v[52:67], v[202:205], v[214:217], v[52:67]
	s_waitcnt vmcnt(23)
	ds_write_b128 v167, v[88:91]
	v_mfma_f32_32x32x16_bf16 v[36:51], v[202:205], v[178:181], v[36:51]
	s_waitcnt vmcnt(22)
	ds_write_b128 v167, v[96:99] offset:36864
	v_mfma_f32_32x32x16_bf16 v[20:35], v[174:177], v[214:217], v[20:35]
	s_waitcnt vmcnt(21)
	ds_write_b128 v190, v[100:103]
	v_mfma_f32_32x32x16_bf16 v[4:19], v[174:177], v[178:181], v[4:19]
	s_waitcnt vmcnt(20)
	ds_write_b128 v190, v[108:111] offset:36864
	s_waitcnt lgkmcnt(4)
	v_mfma_f32_32x32x16_bf16 v[52:67], v[206:209], v[218:221], v[52:67]
	s_waitcnt vmcnt(19)
	ds_write_b128 v191, v[116:119]
	v_mfma_f32_32x32x16_bf16 v[36:51], v[206:209], v[222:225], v[36:51]
	s_waitcnt vmcnt(18)
	ds_write_b128 v191, v[120:123] offset:36864
	v_mfma_f32_32x32x16_bf16 v[20:35], v[210:213], v[218:221], v[20:35]
	s_waitcnt vmcnt(17)
	ds_write_b128 v192, v[124:127]
	v_mfma_f32_32x32x16_bf16 v[4:19], v[210:213], v[222:225], v[4:19]
	s_waitcnt vmcnt(16)
	ds_write_b128 v192, v[128:131] offset:36864
	s_waitcnt lgkmcnt(0)
	s_barrier
	global_load_dwordx4 v[88:91], v[164:165], off offset:896
	global_load_dwordx4 v[96:99], v[162:163], off offset:896
	global_load_dwordx4 v[100:103], v[160:161], off offset:896
	global_load_dwordx4 v[108:111], v[158:159], off offset:896
	global_load_dwordx4 v[116:119], v[156:157], off offset:896
	global_load_dwordx4 v[120:123], v[154:155], off offset:896
	global_load_dwordx4 v[124:127], v[152:153], off offset:896
	global_load_dwordx4 v[128:131], v[146:147], off offset:896
	ds_read_b128 v[174:177], v194
	ds_read_b128 v[178:181], v194 offset:32
	ds_read_b128 v[202:205], v194 offset:4608
	ds_read_b128 v[206:209], v194 offset:4640
	ds_read_b128 v[210:213], v195 offset:36864
	ds_read_b128 v[214:217], v195 offset:36896
	ds_read_b128 v[218:221], v195 offset:41472
	ds_read_b128 v[222:225], v195 offset:41504
	s_waitcnt lgkmcnt(3)
	v_mfma_f32_32x32x16_bf16 v[52:67], v[174:177], v[210:213], v[52:67]
	s_waitcnt lgkmcnt(1)
	v_mfma_f32_32x32x16_bf16 v[36:51], v[174:177], v[218:221], v[36:51]
	v_mfma_f32_32x32x16_bf16 v[4:19], v[202:205], v[218:221], v[4:19]
	s_waitcnt lgkmcnt(0)
	v_mfma_f32_32x32x16_bf16 v[36:51], v[178:181], v[222:225], v[36:51]
	v_mfma_f32_32x32x16_bf16 v[4:19], v[206:209], v[222:225], v[4:19]
	ds_read_b128 v[222:225], v195 offset:41568
	ds_read_b128 v[174:177], v194 offset:4672
	v_mfma_f32_32x32x16_bf16 v[20:35], v[202:205], v[210:213], v[20:35]
	ds_read_b128 v[210:213], v194 offset:4704
	ds_read_b128 v[202:205], v194 offset:64
	v_mfma_f32_32x32x16_bf16 v[52:67], v[178:181], v[214:217], v[52:67]
	ds_read_b128 v[218:221], v195 offset:36960
	ds_read_b128 v[178:181], v195 offset:41536
	v_mfma_f32_32x32x16_bf16 v[20:35], v[206:209], v[214:217], v[20:35]
	ds_read_b128 v[214:217], v195 offset:36928
	ds_read_b128 v[206:209], v194 offset:96
	s_waitcnt lgkmcnt(1)
	v_mfma_f32_32x32x16_bf16 v[52:67], v[202:205], v[214:217], v[52:67]
	s_waitcnt vmcnt(23)
	ds_write_b128 v167, v[132:135] offset:18432
	v_mfma_f32_32x32x16_bf16 v[36:51], v[202:205], v[178:181], v[36:51]
	s_waitcnt vmcnt(22)
	ds_write_b128 v167, v[136:139] offset:55296
	v_mfma_f32_32x32x16_bf16 v[20:35], v[174:177], v[214:217], v[20:35]
	s_waitcnt vmcnt(21)
	ds_write_b128 v190, v[140:143] offset:18432
	v_mfma_f32_32x32x16_bf16 v[4:19], v[174:177], v[178:181], v[4:19]
	s_waitcnt vmcnt(20)
	ds_write_b128 v190, v[198:201] offset:55296
	s_waitcnt lgkmcnt(4)
	v_mfma_f32_32x32x16_bf16 v[52:67], v[206:209], v[218:221], v[52:67]
	s_waitcnt vmcnt(19)
	ds_write_b128 v191, v[226:229] offset:18432
	v_mfma_f32_32x32x16_bf16 v[36:51], v[206:209], v[222:225], v[36:51]
	s_waitcnt vmcnt(18)
	ds_write_b128 v191, v[230:233] offset:55296
	v_mfma_f32_32x32x16_bf16 v[20:35], v[210:213], v[218:221], v[20:35]
	s_waitcnt vmcnt(17)
	ds_write_b128 v192, v[242:245] offset:18432
	v_mfma_f32_32x32x16_bf16 v[4:19], v[210:213], v[222:225], v[4:19]
	s_waitcnt vmcnt(16)
	ds_write_b128 v192, v[246:249] offset:55296
	s_waitcnt lgkmcnt(0)
	s_barrier
; #define MFMA(a, b, c) __builtin_amdgcn_mfma_f32_32x32x16_bf16((a), (b), (c), 0, 0, 0)
; template <class Epi, class ColV>
; DI void gemm_tile(const bf16_t* __restrict__ A, int lda, const bf16_t* __restrict__ Bt, int ldb, int K, int m0, int n0, unsigned char* smem, Epi epi, ColV colv, const bf16_t* __restrict__ HYT = nullptr) {
;     ...
;     auto step = [&](int kt, u32x4 (&ldset)[8], const u32x4 (&stset)[8]) {
;         const int buf = kt & 1;
;         if (kt + 2 < nk) gload(ldset, kt + 2);
;         const bf16_t* Ab = As + (buf * 128 + 64 * wr + li) * LS + 8 * lh;
;         const bf16_t* Bb = Bs + (buf * 128 + 64 * wc + li) * LS + 8 * lh;
;         bf16x8 fa[2][2], fb[2][2], ga[2][2], gb[2][2];
; #pragma unroll
;         for (int k2 = 0; k2 < 2; ++k2) { fa[k2][0] = ld8(Ab + 16 * k2); fa[k2][1] = ld8(Ab + 32 * LS + 16 * k2); fb[k2][0] = ld8(Bb + 16 * k2); fb[k2][1] = ld8(Bb + 32 * LS + 16 * k2); }
;         __builtin_amdgcn_sched_barrier(0);
; #pragma unroll
;         for (int k2 = 0; k2 < 2; ++k2) {
;             acc[0][0] = MFMA(fa[k2][0], fb[k2][0], acc[0][0]); acc[0][1] = MFMA(fa[k2][0], fb[k2][1], acc[0][1]);
;             acc[1][0] = MFMA(fa[k2][1], fb[k2][0], acc[1][0]); acc[1][1] = MFMA(fa[k2][1], fb[k2][1], acc[1][1]);
;         }
; #pragma unroll
;         for (int k2 = 0; k2 < 2; ++k2) { const int ks = 2 + k2; ga[k2][0] = ld8(Ab + 16 * ks); ga[k2][1] = ld8(Ab + 32 * LS + 16 * ks); gb[k2][0] = ld8(Bb + 16 * ks); gb[k2][1] = ld8(Bb + 32 * LS + 16 * ks); }
; #pragma unroll
;         for (int k2 = 0; k2 < 2; ++k2) {
;             acc[0][0] = MFMA(ga[k2][0], gb[k2][0], acc[0][0]); acc[0][1] = MFMA(ga[k2][0], gb[k2][1], acc[0][1]);
;             acc[1][0] = MFMA(ga[k2][1], gb[k2][0], acc[1][0]); acc[1][1] = MFMA(ga[k2][1], gb[k2][1], acc[1][1]);
;         }
;         if (kt + 1 < nk) sstore(stset, buf ^ 1, kt + 1);
; #pragma unroll
;         for (int i = 0; i < 8; ++i) { __builtin_amdgcn_sched_group_barrier(0x008, 1, 0); __builtin_amdgcn_sched_group_barrier(0x100, 1, 0); }
; #pragma unroll
;         for (int i = 0; i < 8; ++i) { __builtin_amdgcn_sched_group_barrier(0x008, 1, 0); __builtin_amdgcn_sched_group_barrier(0x200, 1, 0); }
;         __builtin_amdgcn_sched_barrier(0);
;         __syncthreads();
	global_load_dwordx4 v[132:135], v[164:165], off offset:1024
	global_load_dwordx4 v[136:139], v[162:163], off offset:1024
	global_load_dwordx4 v[140:143], v[160:161], off offset:1024
	global_load_dwordx4 v[198:201], v[158:159], off offset:1024
	global_load_dwordx4 v[226:229], v[156:157], off offset:1024
	global_load_dwordx4 v[230:233], v[154:155], off offset:1024
	global_load_dwordx4 v[242:245], v[152:153], off offset:1024
	global_load_dwordx4 v[246:249], v[146:147], off offset:1024
	ds_read_b128 v[174:177], v196
	ds_read_b128 v[178:181], v196 offset:32
	ds_read_b128 v[202:205], v196 offset:4608
	ds_read_b128 v[206:209], v196 offset:4640
	ds_read_b128 v[210:213], v197 offset:36864
	ds_read_b128 v[214:217], v197 offset:36896
	ds_read_b128 v[218:221], v197 offset:41472
	ds_read_b128 v[222:225], v197 offset:41504
	s_waitcnt lgkmcnt(3)
	v_mfma_f32_32x32x16_bf16 v[52:67], v[174:177], v[210:213], v[52:67]
	s_waitcnt lgkmcnt(1)
	v_mfma_f32_32x32x16_bf16 v[36:51], v[174:177], v[218:221], v[36:51]
	v_mfma_f32_32x32x16_bf16 v[4:19], v[202:205], v[218:221], v[4:19]
	s_waitcnt lgkmcnt(0)
	v_mfma_f32_32x32x16_bf16 v[36:51], v[178:181], v[222:225], v[36:51]
	v_mfma_f32_32x32x16_bf16 v[4:19], v[206:209], v[222:225], v[4:19]
	ds_read_b128 v[222:225], v197 offset:41568
	ds_read_b128 v[174:177], v196 offset:4672
	v_mfma_f32_32x32x16_bf16 v[20:35], v[202:205], v[210:213], v[20:35]
	ds_read_b128 v[210:213], v196 offset:4704
	ds_read_b128 v[202:205], v196 offset:64
	v_mfma_f32_32x32x16_bf16 v[52:67], v[178:181], v[214:217], v[52:67]
	ds_read_b128 v[218:221], v197 offset:36960
	ds_read_b128 v[178:181], v197 offset:41536
	v_mfma_f32_32x32x16_bf16 v[20:35], v[206:209], v[214:217], v[20:35]
	ds_read_b128 v[214:217], v197 offset:36928
	ds_read_b128 v[206:209], v196 offset:96
	s_waitcnt lgkmcnt(1)
	v_mfma_f32_32x32x16_bf16 v[52:67], v[202:205], v[214:217], v[52:67]
	s_waitcnt vmcnt(23)
	ds_write_b128 v167, v[68:71]
	v_mfma_f32_32x32x16_bf16 v[36:51], v[202:205], v[178:181], v[36:51]
	s_waitcnt vmcnt(22)
	ds_write_b128 v167, v[72:75] offset:36864
	v_mfma_f32_32x32x16_bf16 v[20:35], v[174:177], v[214:217], v[20:35]
	s_waitcnt vmcnt(21)
	ds_write_b128 v190, v[76:79]
	v_mfma_f32_32x32x16_bf16 v[4:19], v[174:177], v[178:181], v[4:19]
	s_waitcnt vmcnt(20)
	ds_write_b128 v190, v[80:83] offset:36864
	s_waitcnt lgkmcnt(4)
	v_mfma_f32_32x32x16_bf16 v[52:67], v[206:209], v[218:221], v[52:67]
	s_waitcnt vmcnt(19)
	ds_write_b128 v191, v[84:87]
	v_mfma_f32_32x32x16_bf16 v[36:51], v[206:209], v[222:225], v[36:51]
	s_waitcnt vmcnt(18)
	ds_write_b128 v191, v[92:95] offset:36864
	v_mfma_f32_32x32x16_bf16 v[20:35], v[210:213], v[218:221], v[20:35]
	s_waitcnt vmcnt(17)
	ds_write_b128 v192, v[104:107]
	v_mfma_f32_32x32x16_bf16 v[4:19], v[210:213], v[222:225], v[4:19]
	s_waitcnt vmcnt(16)
	ds_write_b128 v192, v[112:115] offset:36864
	s_waitcnt lgkmcnt(0)
	s_barrier
	global_load_dwordx4 v[68:71], v[164:165], off offset:1152
	global_load_dwordx4 v[72:75], v[162:163], off offset:1152
	global_load_dwordx4 v[76:79], v[160:161], off offset:1152
	global_load_dwordx4 v[80:83], v[158:159], off offset:1152
	global_load_dwordx4 v[84:87], v[156:157], off offset:1152
	global_load_dwordx4 v[92:95], v[154:155], off offset:1152
	global_load_dwordx4 v[104:107], v[152:153], off offset:1152
	global_load_dwordx4 v[112:115], v[146:147], off offset:1152
	ds_read_b128 v[174:177], v194
	ds_read_b128 v[178:181], v194 offset:32
	ds_read_b128 v[202:205], v194 offset:4608
	ds_read_b128 v[206:209], v194 offset:4640
	ds_read_b128 v[210:213], v195 offset:36864
	ds_read_b128 v[214:217], v195 offset:36896
	ds_read_b128 v[218:221], v195 offset:41472
	ds_read_b128 v[222:225], v195 offset:41504
	s_waitcnt lgkmcnt(3)
	v_mfma_f32_32x32x16_bf16 v[52:67], v[174:177], v[210:213], v[52:67]
	s_waitcnt lgkmcnt(1)
	v_mfma_f32_32x32x16_bf16 v[36:51], v[174:177], v[218:221], v[36:51]
	v_mfma_f32_32x32x16_bf16 v[4:19], v[202:205], v[218:221], v[4:19]
	s_waitcnt lgkmcnt(0)
	v_mfma_f32_32x32x16_bf16 v[36:51], v[178:181], v[222:225], v[36:51]
	v_mfma_f32_32x32x16_bf16 v[4:19], v[206:209], v[222:225], v[4:19]
	ds_read_b128 v[222:225], v195 offset:41568
	ds_read_b128 v[174:177], v194 offset:4672
	v_mfma_f32_32x32x16_bf16 v[20:35], v[202:205], v[210:213], v[20:35]
	ds_read_b128 v[210:213], v194 offset:4704
	ds_read_b128 v[202:205], v194 offset:64
	v_mfma_f32_32x32x16_bf16 v[52:67], v[178:181], v[214:217], v[52:67]
	ds_read_b128 v[218:221], v195 offset:36960
	ds_read_b128 v[178:181], v195 offset:41536
	v_mfma_f32_32x32x16_bf16 v[20:35], v[206:209], v[214:217], v[20:35]
	ds_read_b128 v[214:217], v195 offset:36928
	ds_read_b128 v[206:209], v194 offset:96
	s_waitcnt lgkmcnt(1)
	v_mfma_f32_32x32x16_bf16 v[52:67], v[202:205], v[214:217], v[52:67]
	s_waitcnt vmcnt(23)
	ds_write_b128 v167, v[88:91] offset:18432
	v_mfma_f32_32x32x16_bf16 v[36:51], v[202:205], v[178:181], v[36:51]
	s_waitcnt vmcnt(22)
	ds_write_b128 v167, v[96:99] offset:55296
	v_mfma_f32_32x32x16_bf16 v[20:35], v[174:177], v[214:217], v[20:35]
	s_waitcnt vmcnt(21)
	ds_write_b128 v190, v[100:103] offset:18432
	v_mfma_f32_32x32x16_bf16 v[4:19], v[174:177], v[178:181], v[4:19]
	s_waitcnt vmcnt(20)
	ds_write_b128 v190, v[108:111] offset:55296
	s_waitcnt lgkmcnt(4)
	v_mfma_f32_32x32x16_bf16 v[52:67], v[206:209], v[218:221], v[52:67]
	s_waitcnt vmcnt(19)
	ds_write_b128 v191, v[116:119] offset:18432
	v_mfma_f32_32x32x16_bf16 v[36:51], v[206:209], v[222:225], v[36:51]
	s_waitcnt vmcnt(18)
	ds_write_b128 v191, v[120:123] offset:55296
	v_mfma_f32_32x32x16_bf16 v[20:35], v[210:213], v[218:221], v[20:35]
	s_waitcnt vmcnt(17)
	ds_write_b128 v192, v[124:127] offset:18432
	v_mfma_f32_32x32x16_bf16 v[4:19], v[210:213], v[222:225], v[4:19]
	s_waitcnt vmcnt(16)
	ds_write_b128 v192, v[128:131] offset:55296
	s_waitcnt lgkmcnt(0)
	s_barrier
; #define MFMA(a, b, c) __builtin_amdgcn_mfma_f32_32x32x16_bf16((a), (b), (c), 0, 0, 0)
; template <class Epi, class ColV>
; DI void gemm_tile(const bf16_t* __restrict__ A, int lda, const bf16_t* __restrict__ Bt, int ldb, int K, int m0, int n0, unsigned char* smem, Epi epi, ColV colv, const bf16_t* __restrict__ HYT = nullptr) {
;     ...
;     auto step = [&](int kt, u32x4 (&ldset)[8], const u32x4 (&stset)[8]) {
;         const int buf = kt & 1;
;         if (kt + 2 < nk) gload(ldset, kt + 2);
;         const bf16_t* Ab = As + (buf * 128 + 64 * wr + li) * LS + 8 * lh;
;         const bf16_t* Bb = Bs + (buf * 128 + 64 * wc + li) * LS + 8 * lh;
;         bf16x8 fa[2][2], fb[2][2], ga[2][2], gb[2][2];
; #pragma unroll
;         for (int k2 = 0; k2 < 2; ++k2) { fa[k2][0] = ld8(Ab + 16 * k2); fa[k2][1] = ld8(Ab + 32 * LS + 16 * k2); fb[k2][0] = ld8(Bb + 16 * k2); fb[k2][1] = ld8(Bb + 32 * LS + 16 * k2); }
;         __builtin_amdgcn_sched_barrier(0);
; #pragma unroll
;         for (int k2 = 0; k2 < 2; ++k2) {
;             acc[0][0] = MFMA(fa[k2][0], fb[k2][0], acc[0][0]); acc[0][1] = MFMA(fa[k2][0], fb[k2][1], acc[0][1]);
;             acc[1][0] = MFMA(fa[k2][1], fb[k2][0], acc[1][0]); acc[1][1] = MFMA(fa[k2][1], fb[k2][1], acc[1][1]);
;         }
; #pragma unroll
;         for (int k2 = 0; k2 < 2; ++k2) { const int ks = 2 + k2; ga[k2][0] = ld8(Ab + 16 * ks); ga[k2][1] = ld8(Ab + 32 * LS + 16 * ks); gb[k2][0] = ld8(Bb + 16 * ks); gb[k2][1] = ld8(Bb + 32 * LS + 16 * ks); }
; #pragma unroll
;         for (int k2 = 0; k2 < 2; ++k2) {
;             acc[0][0] = MFMA(ga[k2][0], gb[k2][0], acc[0][0]); acc[0][1] = MFMA(ga[k2][0], gb[k2][1], acc[0][1]);
;             acc[1][0] = MFMA(ga[k2][1], gb[k2][0], acc[1][0]); acc[1][1] = MFMA(ga[k2][1], gb[k2][1], acc[1][1]);
;         }
;         if (kt + 1 < nk) sstore(stset, buf ^ 1, kt + 1);
; #pragma unroll
;         for (int i = 0; i < 8; ++i) { __builtin_amdgcn_sched_group_barrier(0x008, 1, 0); __builtin_amdgcn_sched_group_barrier(0x100, 1, 0); }
; #pragma unroll
;         for (int i = 0; i < 8; ++i) { __builtin_amdgcn_sched_group_barrier(0x008, 1, 0); __builtin_amdgcn_sched_group_barrier(0x200, 1, 0); }
;         __builtin_amdgcn_sched_barrier(0);
;         __syncthreads();
	global_load_dwordx4 v[88:91], v[164:165], off offset:1280
	global_load_dwordx4 v[96:99], v[162:163], off offset:1280
	global_load_dwordx4 v[100:103], v[160:161], off offset:1280
	global_load_dwordx4 v[108:111], v[158:159], off offset:1280
	global_load_dwordx4 v[116:119], v[156:157], off offset:1280
	global_load_dwordx4 v[120:123], v[154:155], off offset:1280
	global_load_dwordx4 v[124:127], v[152:153], off offset:1280
	global_load_dwordx4 v[128:131], v[146:147], off offset:1280
	ds_read_b128 v[174:177], v196
	ds_read_b128 v[178:181], v196 offset:32
	ds_read_b128 v[202:205], v196 offset:4608
	ds_read_b128 v[206:209], v196 offset:4640
	ds_read_b128 v[210:213], v197 offset:36864
	ds_read_b128 v[214:217], v197 offset:36896
	ds_read_b128 v[218:221], v197 offset:41472
	ds_read_b128 v[222:225], v197 offset:41504
	s_waitcnt lgkmcnt(3)
	v_mfma_f32_32x32x16_bf16 v[52:67], v[174:177], v[210:213], v[52:67]
	s_waitcnt lgkmcnt(1)
	v_mfma_f32_32x32x16_bf16 v[36:51], v[174:177], v[218:221], v[36:51]
	v_mfma_f32_32x32x16_bf16 v[4:19], v[202:205], v[218:221], v[4:19]
	s_waitcnt lgkmcnt(0)
	v_mfma_f32_32x32x16_bf16 v[36:51], v[178:181], v[222:225], v[36:51]
	v_mfma_f32_32x32x16_bf16 v[4:19], v[206:209], v[222:225], v[4:19]
	ds_read_b128 v[222:225], v197 offset:41568
	ds_read_b128 v[174:177], v196 offset:4672
	v_mfma_f32_32x32x16_bf16 v[20:35], v[202:205], v[210:213], v[20:35]
	ds_read_b128 v[210:213], v196 offset:4704
	ds_read_b128 v[202:205], v196 offset:64
	v_mfma_f32_32x32x16_bf16 v[52:67], v[178:181], v[214:217], v[52:67]
	ds_read_b128 v[218:221], v197 offset:36960
	ds_read_b128 v[178:181], v197 offset:41536
	v_mfma_f32_32x32x16_bf16 v[20:35], v[206:209], v[214:217], v[20:35]
	ds_read_b128 v[214:217], v197 offset:36928
	ds_read_b128 v[206:209], v196 offset:96
	s_waitcnt lgkmcnt(1)
	v_mfma_f32_32x32x16_bf16 v[52:67], v[202:205], v[214:217], v[52:67]
	s_waitcnt vmcnt(23)
	ds_write_b128 v167, v[132:135]
	v_mfma_f32_32x32x16_bf16 v[36:51], v[202:205], v[178:181], v[36:51]
	s_waitcnt vmcnt(22)
	ds_write_b128 v167, v[136:139] offset:36864
	v_mfma_f32_32x32x16_bf16 v[20:35], v[174:177], v[214:217], v[20:35]
	s_waitcnt vmcnt(21)
	ds_write_b128 v190, v[140:143]
	v_mfma_f32_32x32x16_bf16 v[4:19], v[174:177], v[178:181], v[4:19]
	s_waitcnt vmcnt(20)
	ds_write_b128 v190, v[198:201] offset:36864
	s_waitcnt lgkmcnt(4)
	v_mfma_f32_32x32x16_bf16 v[52:67], v[206:209], v[218:221], v[52:67]
	s_waitcnt vmcnt(19)
	ds_write_b128 v191, v[226:229]
	v_mfma_f32_32x32x16_bf16 v[36:51], v[206:209], v[222:225], v[36:51]
	s_waitcnt vmcnt(18)
	ds_write_b128 v191, v[230:233] offset:36864
	v_mfma_f32_32x32x16_bf16 v[20:35], v[210:213], v[218:221], v[20:35]
	s_waitcnt vmcnt(17)
	ds_write_b128 v192, v[242:245]
	v_mfma_f32_32x32x16_bf16 v[4:19], v[210:213], v[222:225], v[4:19]
	s_waitcnt vmcnt(16)
	ds_write_b128 v192, v[246:249] offset:36864
	s_waitcnt lgkmcnt(0)
	s_barrier
	global_load_dwordx4 v[132:135], v[164:165], off offset:1408
	global_load_dwordx4 v[136:139], v[162:163], off offset:1408
	global_load_dwordx4 v[140:143], v[160:161], off offset:1408
	global_load_dwordx4 v[198:201], v[158:159], off offset:1408
	global_load_dwordx4 v[226:229], v[156:157], off offset:1408
	global_load_dwordx4 v[230:233], v[154:155], off offset:1408
	global_load_dwordx4 v[242:245], v[152:153], off offset:1408
	global_load_dwordx4 v[246:249], v[146:147], off offset:1408
	ds_read_b128 v[174:177], v194
	ds_read_b128 v[178:181], v194 offset:32
	ds_read_b128 v[202:205], v194 offset:4608
	ds_read_b128 v[206:209], v194 offset:4640
	ds_read_b128 v[210:213], v195 offset:36864
	ds_read_b128 v[214:217], v195 offset:36896
	ds_read_b128 v[218:221], v195 offset:41472
	ds_read_b128 v[222:225], v195 offset:41504
	s_waitcnt lgkmcnt(3)
	v_mfma_f32_32x32x16_bf16 v[52:67], v[174:177], v[210:213], v[52:67]
	s_waitcnt lgkmcnt(1)
	v_mfma_f32_32x32x16_bf16 v[36:51], v[174:177], v[218:221], v[36:51]
	v_mfma_f32_32x32x16_bf16 v[4:19], v[202:205], v[218:221], v[4:19]
	s_waitcnt lgkmcnt(0)
	v_mfma_f32_32x32x16_bf16 v[36:51], v[178:181], v[222:225], v[36:51]
	v_mfma_f32_32x32x16_bf16 v[4:19], v[206:209], v[222:225], v[4:19]
	ds_read_b128 v[222:225], v195 offset:41568
	ds_read_b128 v[174:177], v194 offset:4672
	v_mfma_f32_32x32x16_bf16 v[20:35], v[202:205], v[210:213], v[20:35]
	ds_read_b128 v[210:213], v194 offset:4704
	ds_read_b128 v[202:205], v194 offset:64
	v_mfma_f32_32x32x16_bf16 v[52:67], v[178:181], v[214:217], v[52:67]
	ds_read_b128 v[218:221], v195 offset:36960
	ds_read_b128 v[178:181], v195 offset:41536
	v_mfma_f32_32x32x16_bf16 v[20:35], v[206:209], v[214:217], v[20:35]
	ds_read_b128 v[214:217], v195 offset:36928
	ds_read_b128 v[206:209], v194 offset:96
	s_waitcnt lgkmcnt(1)
	v_mfma_f32_32x32x16_bf16 v[52:67], v[202:205], v[214:217], v[52:67]
	s_waitcnt vmcnt(23)
	ds_write_b128 v167, v[68:71] offset:18432
	v_mfma_f32_32x32x16_bf16 v[36:51], v[202:205], v[178:181], v[36:51]
	s_waitcnt vmcnt(22)
	ds_write_b128 v167, v[72:75] offset:55296
	v_mfma_f32_32x32x16_bf16 v[20:35], v[174:177], v[214:217], v[20:35]
	s_waitcnt vmcnt(21)
	ds_write_b128 v190, v[76:79] offset:18432
	v_mfma_f32_32x32x16_bf16 v[4:19], v[174:177], v[178:181], v[4:19]
	s_waitcnt vmcnt(20)
	ds_write_b128 v190, v[80:83] offset:55296
	s_waitcnt lgkmcnt(4)
	v_mfma_f32_32x32x16_bf16 v[52:67], v[206:209], v[218:221], v[52:67]
	s_waitcnt vmcnt(19)
	ds_write_b128 v191, v[84:87] offset:18432
	v_mfma_f32_32x32x16_bf16 v[36:51], v[206:209], v[222:225], v[36:51]
	s_waitcnt vmcnt(18)
	ds_write_b128 v191, v[92:95] offset:55296
	v_mfma_f32_32x32x16_bf16 v[20:35], v[210:213], v[218:221], v[20:35]
	s_waitcnt vmcnt(17)
	ds_write_b128 v192, v[104:107] offset:18432
	v_mfma_f32_32x32x16_bf16 v[4:19], v[210:213], v[222:225], v[4:19]
	s_waitcnt vmcnt(16)
	ds_write_b128 v192, v[112:115] offset:55296
	s_waitcnt lgkmcnt(0)
	s_barrier
; #define MFMA(a, b, c) __builtin_amdgcn_mfma_f32_32x32x16_bf16((a), (b), (c), 0, 0, 0)
; template <class Epi, class ColV>
; DI void gemm_tile(const bf16_t* __restrict__ A, int lda, const bf16_t* __restrict__ Bt, int ldb, int K, int m0, int n0, unsigned char* smem, Epi epi, ColV colv, const bf16_t* __restrict__ HYT = nullptr) {
;     ...
;     auto step = [&](int kt, u32x4 (&ldset)[8], const u32x4 (&stset)[8]) {
;         const int buf = kt & 1;
;         if (kt + 2 < nk) gload(ldset, kt + 2);
;         const bf16_t* Ab = As + (buf * 128 + 64 * wr + li) * LS + 8 * lh;
;         const bf16_t* Bb = Bs + (buf * 128 + 64 * wc + li) * LS + 8 * lh;
;         bf16x8 fa[2][2], fb[2][2], ga[2][2], gb[2][2];
; #pragma unroll
;         for (int k2 = 0; k2 < 2; ++k2) { fa[k2][0] = ld8(Ab + 16 * k2); fa[k2][1] = ld8(Ab + 32 * LS + 16 * k2); fb[k2][0] = ld8(Bb + 16 * k2); fb[k2][1] = ld8(Bb + 32 * LS + 16 * k2); }
;         __builtin_amdgcn_sched_barrier(0);
; #pragma unroll
;         for (int k2 = 0; k2 < 2; ++k2) {
;             acc[0][0] = MFMA(fa[k2][0], fb[k2][0], acc[0][0]); acc[0][1] = MFMA(fa[k2][0], fb[k2][1], acc[0][1]);
;             acc[1][0] = MFMA(fa[k2][1], fb[k2][0], acc[1][0]); acc[1][1] = MFMA(fa[k2][1], fb[k2][1], acc[1][1]);
;         }
; #pragma unroll
;         for (int k2 = 0; k2 < 2; ++k2) { const int ks = 2 + k2; ga[k2][0] = ld8(Ab + 16 * ks); ga[k2][1] = ld8(Ab + 32 * LS + 16 * ks); gb[k2][0] = ld8(Bb + 16 * ks); gb[k2][1] = ld8(Bb + 32 * LS + 16 * ks); }
; #pragma unroll
;         for (int k2 = 0; k2 < 2; ++k2) {
;             acc[0][0] = MFMA(ga[k2][0], gb[k2][0], acc[0][0]); acc[0][1] = MFMA(ga[k2][0], gb[k2][1], acc[0][1]);
;             acc[1][0] = MFMA(ga[k2][1], gb[k2][0], acc[1][0]); acc[1][1] = MFMA(ga[k2][1], gb[k2][1], acc[1][1]);
;         }
;         if (kt + 1 < nk) sstore(stset, buf ^ 1, kt + 1);
; #pragma unroll
;         for (int i = 0; i < 8; ++i) { __builtin_amdgcn_sched_group_barrier(0x008, 1, 0); __builtin_amdgcn_sched_group_barrier(0x100, 1, 0); }
; #pragma unroll
;         for (int i = 0; i < 8; ++i) { __builtin_amdgcn_sched_group_barrier(0x008, 1, 0); __builtin_amdgcn_sched_group_barrier(0x200, 1, 0); }
;         __builtin_amdgcn_sched_barrier(0);
;         __syncthreads();
	global_load_dwordx4 v[68:71], v[164:165], off offset:1536
	global_load_dwordx4 v[72:75], v[162:163], off offset:1536
	global_load_dwordx4 v[76:79], v[160:161], off offset:1536
	global_load_dwordx4 v[80:83], v[158:159], off offset:1536
	global_load_dwordx4 v[84:87], v[156:157], off offset:1536
	global_load_dwordx4 v[92:95], v[154:155], off offset:1536
	global_load_dwordx4 v[104:107], v[152:153], off offset:1536
	global_load_dwordx4 v[112:115], v[146:147], off offset:1536
	ds_read_b128 v[174:177], v196
	ds_read_b128 v[178:181], v196 offset:32
	ds_read_b128 v[202:205], v196 offset:4608
	ds_read_b128 v[206:209], v196 offset:4640
	ds_read_b128 v[210:213], v197 offset:36864
	ds_read_b128 v[214:217], v197 offset:36896
	ds_read_b128 v[218:221], v197 offset:41472
	ds_read_b128 v[222:225], v197 offset:41504
	s_waitcnt lgkmcnt(3)
	v_mfma_f32_32x32x16_bf16 v[52:67], v[174:177], v[210:213], v[52:67]
	s_waitcnt lgkmcnt(1)
	v_mfma_f32_32x32x16_bf16 v[36:51], v[174:177], v[218:221], v[36:51]
	v_mfma_f32_32x32x16_bf16 v[4:19], v[202:205], v[218:221], v[4:19]
	s_waitcnt lgkmcnt(0)
	v_mfma_f32_32x32x16_bf16 v[36:51], v[178:181], v[222:225], v[36:51]
	v_mfma_f32_32x32x16_bf16 v[4:19], v[206:209], v[222:225], v[4:19]
	ds_read_b128 v[222:225], v197 offset:41568
	ds_read_b128 v[174:177], v196 offset:4672
	v_mfma_f32_32x32x16_bf16 v[20:35], v[202:205], v[210:213], v[20:35]
	ds_read_b128 v[210:213], v196 offset:4704
	ds_read_b128 v[202:205], v196 offset:64
	v_mfma_f32_32x32x16_bf16 v[52:67], v[178:181], v[214:217], v[52:67]
	ds_read_b128 v[218:221], v197 offset:36960
	ds_read_b128 v[178:181], v197 offset:41536
	v_mfma_f32_32x32x16_bf16 v[20:35], v[206:209], v[214:217], v[20:35]
	ds_read_b128 v[214:217], v197 offset:36928
	ds_read_b128 v[206:209], v196 offset:96
	s_waitcnt lgkmcnt(1)
	v_mfma_f32_32x32x16_bf16 v[52:67], v[202:205], v[214:217], v[52:67]
	s_waitcnt vmcnt(23)
	ds_write_b128 v167, v[88:91]
	v_mfma_f32_32x32x16_bf16 v[36:51], v[202:205], v[178:181], v[36:51]
	s_waitcnt vmcnt(22)
	ds_write_b128 v167, v[96:99] offset:36864
	v_mfma_f32_32x32x16_bf16 v[20:35], v[174:177], v[214:217], v[20:35]
	s_waitcnt vmcnt(21)
	ds_write_b128 v190, v[100:103]
	v_mfma_f32_32x32x16_bf16 v[4:19], v[174:177], v[178:181], v[4:19]
	s_waitcnt vmcnt(20)
	ds_write_b128 v190, v[108:111] offset:36864
	s_waitcnt lgkmcnt(4)
	v_mfma_f32_32x32x16_bf16 v[52:67], v[206:209], v[218:221], v[52:67]
	s_waitcnt vmcnt(19)
	ds_write_b128 v191, v[116:119]
	v_mfma_f32_32x32x16_bf16 v[36:51], v[206:209], v[222:225], v[36:51]
	s_waitcnt vmcnt(18)
	ds_write_b128 v191, v[120:123] offset:36864
	v_mfma_f32_32x32x16_bf16 v[20:35], v[210:213], v[218:221], v[20:35]
	s_waitcnt vmcnt(17)
	ds_write_b128 v192, v[124:127]
	v_mfma_f32_32x32x16_bf16 v[4:19], v[210:213], v[222:225], v[4:19]
	s_waitcnt vmcnt(16)
	ds_write_b128 v192, v[128:131] offset:36864
	s_waitcnt lgkmcnt(0)
	s_barrier
	global_load_dwordx4 v[88:91], v[164:165], off offset:1664
	global_load_dwordx4 v[96:99], v[162:163], off offset:1664
	global_load_dwordx4 v[100:103], v[160:161], off offset:1664
	global_load_dwordx4 v[108:111], v[158:159], off offset:1664
	global_load_dwordx4 v[116:119], v[156:157], off offset:1664
	global_load_dwordx4 v[120:123], v[154:155], off offset:1664
	global_load_dwordx4 v[124:127], v[152:153], off offset:1664
	global_load_dwordx4 v[128:131], v[146:147], off offset:1664
	ds_read_b128 v[174:177], v194
	ds_read_b128 v[178:181], v194 offset:32
	ds_read_b128 v[202:205], v194 offset:4608
	ds_read_b128 v[206:209], v194 offset:4640
	ds_read_b128 v[210:213], v195 offset:36864
	ds_read_b128 v[214:217], v195 offset:36896
	ds_read_b128 v[218:221], v195 offset:41472
	ds_read_b128 v[222:225], v195 offset:41504
	s_waitcnt lgkmcnt(3)
	v_mfma_f32_32x32x16_bf16 v[52:67], v[174:177], v[210:213], v[52:67]
	s_waitcnt lgkmcnt(1)
	v_mfma_f32_32x32x16_bf16 v[36:51], v[174:177], v[218:221], v[36:51]
	v_mfma_f32_32x32x16_bf16 v[4:19], v[202:205], v[218:221], v[4:19]
	s_waitcnt lgkmcnt(0)
	v_mfma_f32_32x32x16_bf16 v[36:51], v[178:181], v[222:225], v[36:51]
	v_mfma_f32_32x32x16_bf16 v[4:19], v[206:209], v[222:225], v[4:19]
	ds_read_b128 v[222:225], v195 offset:41568
	ds_read_b128 v[174:177], v194 offset:4672
	v_mfma_f32_32x32x16_bf16 v[20:35], v[202:205], v[210:213], v[20:35]
	ds_read_b128 v[210:213], v194 offset:4704
	ds_read_b128 v[202:205], v194 offset:64
	v_mfma_f32_32x32x16_bf16 v[52:67], v[178:181], v[214:217], v[52:67]
	ds_read_b128 v[218:221], v195 offset:36960
	ds_read_b128 v[178:181], v195 offset:41536
	v_mfma_f32_32x32x16_bf16 v[20:35], v[206:209], v[214:217], v[20:35]
	ds_read_b128 v[214:217], v195 offset:36928
	ds_read_b128 v[206:209], v194 offset:96
	s_waitcnt lgkmcnt(1)
	v_mfma_f32_32x32x16_bf16 v[52:67], v[202:205], v[214:217], v[52:67]
	s_waitcnt vmcnt(23)
	ds_write_b128 v167, v[132:135] offset:18432
	v_mfma_f32_32x32x16_bf16 v[36:51], v[202:205], v[178:181], v[36:51]
	s_waitcnt vmcnt(22)
	ds_write_b128 v167, v[136:139] offset:55296
	v_mfma_f32_32x32x16_bf16 v[20:35], v[174:177], v[214:217], v[20:35]
	s_waitcnt vmcnt(21)
	ds_write_b128 v190, v[140:143] offset:18432
	v_mfma_f32_32x32x16_bf16 v[4:19], v[174:177], v[178:181], v[4:19]
	s_waitcnt vmcnt(20)
	ds_write_b128 v190, v[198:201] offset:55296
	s_waitcnt lgkmcnt(4)
	v_mfma_f32_32x32x16_bf16 v[52:67], v[206:209], v[218:221], v[52:67]
	s_waitcnt vmcnt(19)
	ds_write_b128 v191, v[226:229] offset:18432
	v_mfma_f32_32x32x16_bf16 v[36:51], v[206:209], v[222:225], v[36:51]
	s_waitcnt vmcnt(18)
	ds_write_b128 v191, v[230:233] offset:55296
	v_mfma_f32_32x32x16_bf16 v[20:35], v[210:213], v[218:221], v[20:35]
	s_waitcnt vmcnt(17)
	ds_write_b128 v192, v[242:245] offset:18432
	v_mfma_f32_32x32x16_bf16 v[4:19], v[210:213], v[222:225], v[4:19]
	s_waitcnt vmcnt(16)
	ds_write_b128 v192, v[246:249] offset:55296
	s_waitcnt lgkmcnt(0)
	s_barrier
; #define MFMA(a, b, c) __builtin_amdgcn_mfma_f32_32x32x16_bf16((a), (b), (c), 0, 0, 0)
; template <class Epi, class ColV>
; DI void gemm_tile(const bf16_t* __restrict__ A, int lda, const bf16_t* __restrict__ Bt, int ldb, int K, int m0, int n0, unsigned char* smem, Epi epi, ColV colv, const bf16_t* __restrict__ HYT = nullptr) {
;     ...
;     auto step = [&](int kt, u32x4 (&ldset)[8], const u32x4 (&stset)[8]) {
;         const int buf = kt & 1;
;         if (kt + 2 < nk) gload(ldset, kt + 2);
;         const bf16_t* Ab = As + (buf * 128 + 64 * wr + li) * LS + 8 * lh;
;         const bf16_t* Bb = Bs + (buf * 128 + 64 * wc + li) * LS + 8 * lh;
;         bf16x8 fa[2][2], fb[2][2], ga[2][2], gb[2][2];
; #pragma unroll
;         for (int k2 = 0; k2 < 2; ++k2) { fa[k2][0] = ld8(Ab + 16 * k2); fa[k2][1] = ld8(Ab + 32 * LS + 16 * k2); fb[k2][0] = ld8(Bb + 16 * k2); fb[k2][1] = ld8(Bb + 32 * LS + 16 * k2); }
;         __builtin_amdgcn_sched_barrier(0);
; #pragma unroll
;         for (int k2 = 0; k2 < 2; ++k2) {
;             acc[0][0] = MFMA(fa[k2][0], fb[k2][0], acc[0][0]); acc[0][1] = MFMA(fa[k2][0], fb[k2][1], acc[0][1]);
;             acc[1][0] = MFMA(fa[k2][1], fb[k2][0], acc[1][0]); acc[1][1] = MFMA(fa[k2][1], fb[k2][1], acc[1][1]);
;         }
; #pragma unroll
;         for (int k2 = 0; k2 < 2; ++k2) { const int ks = 2 + k2; ga[k2][0] = ld8(Ab + 16 * ks); ga[k2][1] = ld8(Ab + 32 * LS + 16 * ks); gb[k2][0] = ld8(Bb + 16 * ks); gb[k2][1] = ld8(Bb + 32 * LS + 16 * ks); }
; #pragma unroll
;         for (int k2 = 0; k2 < 2; ++k2) {
;             acc[0][0] = MFMA(ga[k2][0], gb[k2][0], acc[0][0]); acc[0][1] = MFMA(ga[k2][0], gb[k2][1], acc[0][1]);
;             acc[1][0] = MFMA(ga[k2][1], gb[k2][0], acc[1][0]); acc[1][1] = MFMA(ga[k2][1], gb[k2][1], acc[1][1]);
;         }
;         if (kt + 1 < nk) sstore(stset, buf ^ 1, kt + 1);
; #pragma unroll
;         for (int i = 0; i < 8; ++i) { __builtin_amdgcn_sched_group_barrier(0x008, 1, 0); __builtin_amdgcn_sched_group_barrier(0x100, 1, 0); }
; #pragma unroll
;         for (int i = 0; i < 8; ++i) { __builtin_amdgcn_sched_group_barrier(0x008, 1, 0); __builtin_amdgcn_sched_group_barrier(0x200, 1, 0); }
;         __builtin_amdgcn_sched_barrier(0);
;         __syncthreads();
	global_load_dwordx4 v[132:135], v[164:165], off offset:1792
	global_load_dwordx4 v[136:139], v[162:163], off offset:1792
	global_load_dwordx4 v[140:143], v[160:161], off offset:1792
	global_load_dwordx4 v[198:201], v[158:159], off offset:1792
	global_load_dwordx4 v[226:229], v[156:157], off offset:1792
	global_load_dwordx4 v[230:233], v[154:155], off offset:1792
	global_load_dwordx4 v[242:245], v[152:153], off offset:1792
	global_load_dwordx4 v[246:249], v[146:147], off offset:1792
	ds_read_b128 v[174:177], v196
	ds_read_b128 v[178:181], v196 offset:32
	ds_read_b128 v[202:205], v196 offset:4608
	ds_read_b128 v[206:209], v196 offset:4640
	ds_read_b128 v[210:213], v197 offset:36864
	ds_read_b128 v[214:217], v197 offset:36896
	ds_read_b128 v[218:221], v197 offset:41472
	ds_read_b128 v[222:225], v197 offset:41504
	s_waitcnt lgkmcnt(3)
	v_mfma_f32_32x32x16_bf16 v[52:67], v[174:177], v[210:213], v[52:67]
	s_waitcnt lgkmcnt(1)
	v_mfma_f32_32x32x16_bf16 v[36:51], v[174:177], v[218:221], v[36:51]
	v_mfma_f32_32x32x16_bf16 v[4:19], v[202:205], v[218:221], v[4:19]
	s_waitcnt lgkmcnt(0)
	v_mfma_f32_32x32x16_bf16 v[36:51], v[178:181], v[222:225], v[36:51]
	v_mfma_f32_32x32x16_bf16 v[4:19], v[206:209], v[222:225], v[4:19]
	ds_read_b128 v[222:225], v197 offset:41568
	ds_read_b128 v[174:177], v196 offset:4672
	v_mfma_f32_32x32x16_bf16 v[20:35], v[202:205], v[210:213], v[20:35]
	ds_read_b128 v[210:213], v196 offset:4704
	ds_read_b128 v[202:205], v196 offset:64
	v_mfma_f32_32x32x16_bf16 v[52:67], v[178:181], v[214:217], v[52:67]
	ds_read_b128 v[218:221], v197 offset:36960
	ds_read_b128 v[178:181], v197 offset:41536
	v_mfma_f32_32x32x16_bf16 v[20:35], v[206:209], v[214:217], v[20:35]
	ds_read_b128 v[214:217], v197 offset:36928
	ds_read_b128 v[206:209], v196 offset:96
	s_waitcnt lgkmcnt(1)
	v_mfma_f32_32x32x16_bf16 v[52:67], v[202:205], v[214:217], v[52:67]
	s_waitcnt vmcnt(23)
	ds_write_b128 v167, v[68:71]
	v_mfma_f32_32x32x16_bf16 v[36:51], v[202:205], v[178:181], v[36:51]
	s_waitcnt vmcnt(22)
	ds_write_b128 v167, v[72:75] offset:36864
	v_mfma_f32_32x32x16_bf16 v[20:35], v[174:177], v[214:217], v[20:35]
	s_waitcnt vmcnt(21)
	ds_write_b128 v190, v[76:79]
	v_mfma_f32_32x32x16_bf16 v[4:19], v[174:177], v[178:181], v[4:19]
	s_waitcnt vmcnt(20)
	ds_write_b128 v190, v[80:83] offset:36864
	s_waitcnt lgkmcnt(4)
	v_mfma_f32_32x32x16_bf16 v[52:67], v[206:209], v[218:221], v[52:67]
	s_waitcnt vmcnt(19)
	ds_write_b128 v191, v[84:87]
	v_mfma_f32_32x32x16_bf16 v[36:51], v[206:209], v[222:225], v[36:51]
	s_waitcnt vmcnt(18)
	ds_write_b128 v191, v[92:95] offset:36864
	v_mfma_f32_32x32x16_bf16 v[20:35], v[210:213], v[218:221], v[20:35]
	s_waitcnt vmcnt(17)
	ds_write_b128 v192, v[104:107]
	v_mfma_f32_32x32x16_bf16 v[4:19], v[210:213], v[222:225], v[4:19]
	s_waitcnt vmcnt(16)
	ds_write_b128 v192, v[112:115] offset:36864
	s_waitcnt lgkmcnt(0)
	s_barrier
	global_load_dwordx4 v[68:71], v[164:165], off offset:1920
	global_load_dwordx4 v[72:75], v[162:163], off offset:1920
	global_load_dwordx4 v[76:79], v[160:161], off offset:1920
	global_load_dwordx4 v[80:83], v[158:159], off offset:1920
	global_load_dwordx4 v[84:87], v[156:157], off offset:1920
	global_load_dwordx4 v[92:95], v[154:155], off offset:1920
	global_load_dwordx4 v[104:107], v[152:153], off offset:1920
	global_load_dwordx4 v[112:115], v[146:147], off offset:1920
	ds_read_b128 v[174:177], v194
	ds_read_b128 v[178:181], v194 offset:32
	ds_read_b128 v[202:205], v194 offset:4608
	ds_read_b128 v[206:209], v194 offset:4640
	ds_read_b128 v[210:213], v195 offset:36864
	ds_read_b128 v[214:217], v195 offset:36896
	ds_read_b128 v[218:221], v195 offset:41472
	ds_read_b128 v[222:225], v195 offset:41504
	s_waitcnt lgkmcnt(3)
	v_mfma_f32_32x32x16_bf16 v[52:67], v[174:177], v[210:213], v[52:67]
	s_waitcnt lgkmcnt(1)
	v_mfma_f32_32x32x16_bf16 v[36:51], v[174:177], v[218:221], v[36:51]
	v_mfma_f32_32x32x16_bf16 v[4:19], v[202:205], v[218:221], v[4:19]
	s_waitcnt lgkmcnt(0)
	v_mfma_f32_32x32x16_bf16 v[36:51], v[178:181], v[222:225], v[36:51]
	v_mfma_f32_32x32x16_bf16 v[4:19], v[206:209], v[222:225], v[4:19]
	ds_read_b128 v[222:225], v195 offset:41568
	ds_read_b128 v[174:177], v194 offset:4672
	v_mfma_f32_32x32x16_bf16 v[20:35], v[202:205], v[210:213], v[20:35]
	ds_read_b128 v[210:213], v194 offset:4704
	ds_read_b128 v[202:205], v194 offset:64
	v_mfma_f32_32x32x16_bf16 v[52:67], v[178:181], v[214:217], v[52:67]
	ds_read_b128 v[218:221], v195 offset:36960
	ds_read_b128 v[178:181], v195 offset:41536
	v_mfma_f32_32x32x16_bf16 v[20:35], v[206:209], v[214:217], v[20:35]
	ds_read_b128 v[214:217], v195 offset:36928
	ds_read_b128 v[206:209], v194 offset:96
	s_waitcnt lgkmcnt(1)
	v_mfma_f32_32x32x16_bf16 v[52:67], v[202:205], v[214:217], v[52:67]
	s_waitcnt vmcnt(23)
	ds_write_b128 v167, v[88:91] offset:18432
	v_mfma_f32_32x32x16_bf16 v[36:51], v[202:205], v[178:181], v[36:51]
	s_waitcnt vmcnt(22)
	ds_write_b128 v167, v[96:99] offset:55296
	v_mfma_f32_32x32x16_bf16 v[20:35], v[174:177], v[214:217], v[20:35]
	s_waitcnt vmcnt(21)
	ds_write_b128 v190, v[100:103] offset:18432
	v_mfma_f32_32x32x16_bf16 v[4:19], v[174:177], v[178:181], v[4:19]
	s_waitcnt vmcnt(20)
	ds_write_b128 v190, v[108:111] offset:55296
	s_waitcnt lgkmcnt(4)
	v_mfma_f32_32x32x16_bf16 v[52:67], v[206:209], v[218:221], v[52:67]
	s_waitcnt vmcnt(19)
	ds_write_b128 v191, v[116:119] offset:18432
	v_mfma_f32_32x32x16_bf16 v[36:51], v[206:209], v[222:225], v[36:51]
	s_waitcnt vmcnt(18)
	ds_write_b128 v191, v[120:123] offset:55296
	v_mfma_f32_32x32x16_bf16 v[20:35], v[210:213], v[218:221], v[20:35]
	s_waitcnt vmcnt(17)
	ds_write_b128 v192, v[124:127] offset:18432
	v_mfma_f32_32x32x16_bf16 v[4:19], v[210:213], v[222:225], v[4:19]
	s_waitcnt vmcnt(16)
	ds_write_b128 v192, v[128:131] offset:55296
	s_waitcnt lgkmcnt(0)
	s_barrier
; template <class Epi, class ColV>
; DI void gemm_tile(const bf16_t* __restrict__ A, int lda, const bf16_t* __restrict__ Bt, int ldb, int K, int m0, int n0, unsigned char* smem, Epi epi, ColV colv, const bf16_t* __restrict__ HYT = nullptr) {
;     ...
;     auto step = [&](int kt, u32x4 (&ldset)[8], const u32x4 (&stset)[8]) {
;         const int buf = kt & 1;
;         if (kt + 2 < nk) gload(ldset, kt + 2);
;         const bf16_t* Ab = As + (buf * 128 + 64 * wr + li) * LS + 8 * lh;
;         const bf16_t* Bb = Bs + (buf * 128 + 64 * wc + li) * LS + 8 * lh;
;         bf16x8 fa[2][2], fb[2][2], ga[2][2], gb[2][2];
; #pragma unroll
;         for (int k2 = 0; k2 < 2; ++k2) { fa[k2][0] = ld8(Ab + 16 * k2); fa[k2][1] = ld8(Ab + 32 * LS + 16 * k2); fb[k2][0] = ld8(Bb + 16 * k2); fb[k2][1] = ld8(Bb + 32 * LS + 16 * k2); }
;         __builtin_amdgcn_sched_barrier(0);
; #pragma unroll
;         for (int k2 = 0; k2 < 2; ++k2) {
;             acc[0][0] = MFMA(fa[k2][0], fb[k2][0], acc[0][0]); acc[0][1] = MFMA(fa[k2][0], fb[k2][1], acc[0][1]);
;             acc[1][0] = MFMA(fa[k2][1], fb[k2][0], acc[1][0]); acc[1][1] = MFMA(fa[k2][1], fb[k2][1], acc[1][1]);
;         }
; #pragma unroll
;         for (int k2 = 0; k2 < 2; ++k2) { const int ks = 2 + k2; ga[k2][0] = ld8(Ab + 16 * ks); ga[k2][1] = ld8(Ab + 32 * LS + 16 * ks); gb[k2][0] = ld8(Bb + 16 * ks); gb[k2][1] = ld8(Bb + 32 * LS + 16 * ks); }
; #pragma unroll
;         for (int k2 = 0; k2 < 2; ++k2) {
;             acc[0][0] = MFMA(ga[k2][0], gb[k2][0], acc[0][0]); acc[0][1] = MFMA(ga[k2][0], gb[k2][1], acc[0][1]);
;             acc[1][0] = MFMA(ga[k2][1], gb[k2][0], acc[1][0]); acc[1][1] = MFMA(ga[k2][1], gb[k2][1], acc[1][1]);
;         }
;         if (kt + 1 < nk) sstore(stset, buf ^ 1, kt + 1);
; #pragma unroll
;         for (int i = 0; i < 8; ++i) { __builtin_amdgcn_sched_group_barrier(0x008, 1, 0); __builtin_amdgcn_sched_group_barrier(0x100, 1, 0); }
; #pragma unroll
;         for (int i = 0; i < 8; ++i) { __builtin_amdgcn_sched_group_barrier(0x008, 1, 0); __builtin_amdgcn_sched_group_barrier(0x200, 1, 0); }
;         __builtin_amdgcn_sched_barrier(0);
;         __syncthreads();
;     };
;     gload(R0, 0); gload(R1, 1);
;     sstore(R0, 0, 0); __syncthreads();
;     for (int kt = 0; kt < nk; kt += 2) {
;         step(kt, R0, R1);
;         if (kt + 1 < nk) step(kt + 1, R1, R0);
;     }
	ds_read_b128 v[174:177], v196
	ds_read_b128 v[178:181], v196 offset:32
	ds_read_b128 v[202:205], v196 offset:4608
	ds_read_b128 v[206:209], v196 offset:4640
	ds_read_b128 v[210:213], v197 offset:36864
	ds_read_b128 v[214:217], v197 offset:36896
	ds_read_b128 v[218:221], v197 offset:41472
	ds_read_b128 v[222:225], v197 offset:41504
	s_waitcnt lgkmcnt(3)
	v_mfma_f32_32x32x16_bf16 v[52:67], v[174:177], v[210:213], v[52:67]
	s_waitcnt lgkmcnt(1)
	v_mfma_f32_32x32x16_bf16 v[36:51], v[174:177], v[218:221], v[36:51]
	v_mfma_f32_32x32x16_bf16 v[4:19], v[202:205], v[218:221], v[4:19]
	s_waitcnt lgkmcnt(0)
	v_mfma_f32_32x32x16_bf16 v[36:51], v[178:181], v[222:225], v[36:51]
	v_mfma_f32_32x32x16_bf16 v[4:19], v[206:209], v[222:225], v[4:19]
	ds_read_b128 v[222:225], v197 offset:41568
	ds_read_b128 v[174:177], v196 offset:4672
	v_mfma_f32_32x32x16_bf16 v[20:35], v[202:205], v[210:213], v[20:35]
	ds_read_b128 v[210:213], v196 offset:4704
	ds_read_b128 v[202:205], v196 offset:64
	v_mfma_f32_32x32x16_bf16 v[52:67], v[178:181], v[214:217], v[52:67]
	ds_read_b128 v[218:221], v197 offset:36960
	ds_read_b128 v[178:181], v197 offset:41536
	v_mfma_f32_32x32x16_bf16 v[20:35], v[206:209], v[214:217], v[20:35]
	ds_read_b128 v[214:217], v197 offset:36928
	ds_read_b128 v[206:209], v196 offset:96
	s_waitcnt lgkmcnt(1)
	v_mfma_f32_32x32x16_bf16 v[52:67], v[202:205], v[214:217], v[52:67]
	s_waitcnt vmcnt(15)
	ds_write_b128 v167, v[132:135]
	v_mfma_f32_32x32x16_bf16 v[36:51], v[202:205], v[178:181], v[36:51]
	s_waitcnt vmcnt(14)
	ds_write_b128 v167, v[136:139] offset:36864
	v_mfma_f32_32x32x16_bf16 v[20:35], v[174:177], v[214:217], v[20:35]
	s_waitcnt vmcnt(13)
	ds_write_b128 v190, v[140:143]
	v_mfma_f32_32x32x16_bf16 v[4:19], v[174:177], v[178:181], v[4:19]
	s_waitcnt vmcnt(12)
	ds_write_b128 v190, v[198:201] offset:36864
	s_waitcnt lgkmcnt(4)
	v_mfma_f32_32x32x16_bf16 v[52:67], v[206:209], v[218:221], v[52:67]
	s_waitcnt vmcnt(11)
	ds_write_b128 v191, v[226:229]
	v_mfma_f32_32x32x16_bf16 v[36:51], v[206:209], v[222:225], v[36:51]
	s_waitcnt vmcnt(10)
	ds_write_b128 v191, v[230:233] offset:36864
	v_mfma_f32_32x32x16_bf16 v[20:35], v[210:213], v[218:221], v[20:35]
	s_waitcnt vmcnt(9)
	ds_write_b128 v192, v[242:245]
	v_mfma_f32_32x32x16_bf16 v[4:19], v[210:213], v[222:225], v[4:19]
	s_waitcnt vmcnt(8)
	ds_write_b128 v192, v[246:249] offset:36864
	s_waitcnt lgkmcnt(0)
	s_barrier
	ds_read_b128 v[174:177], v194
	ds_read_b128 v[178:181], v194 offset:32
	ds_read_b128 v[202:205], v194 offset:4608
	ds_read_b128 v[206:209], v194 offset:4640
	ds_read_b128 v[210:213], v195 offset:36864
	ds_read_b128 v[214:217], v195 offset:36896
	ds_read_b128 v[218:221], v195 offset:41472
	ds_read_b128 v[222:225], v195 offset:41504
	s_waitcnt lgkmcnt(3)
	v_mfma_f32_32x32x16_bf16 v[52:67], v[174:177], v[210:213], v[52:67]
	s_waitcnt lgkmcnt(1)
	v_mfma_f32_32x32x16_bf16 v[36:51], v[174:177], v[218:221], v[36:51]
	v_mfma_f32_32x32x16_bf16 v[4:19], v[202:205], v[218:221], v[4:19]
	s_waitcnt lgkmcnt(0)
	v_mfma_f32_32x32x16_bf16 v[36:51], v[178:181], v[222:225], v[36:51]
	v_mfma_f32_32x32x16_bf16 v[4:19], v[206:209], v[222:225], v[4:19]
	ds_read_b128 v[222:225], v195 offset:41568
	ds_read_b128 v[174:177], v194 offset:4672
	v_mfma_f32_32x32x16_bf16 v[20:35], v[202:205], v[210:213], v[20:35]
	ds_read_b128 v[210:213], v194 offset:4704
	ds_read_b128 v[202:205], v194 offset:64
	v_mfma_f32_32x32x16_bf16 v[52:67], v[178:181], v[214:217], v[52:67]
	ds_read_b128 v[218:221], v195 offset:36960
	ds_read_b128 v[178:181], v195 offset:41536
	v_mfma_f32_32x32x16_bf16 v[20:35], v[206:209], v[214:217], v[20:35]
	ds_read_b128 v[214:217], v195 offset:36928
	ds_read_b128 v[206:209], v194 offset:96
	s_waitcnt lgkmcnt(1)
	v_mfma_f32_32x32x16_bf16 v[52:67], v[202:205], v[214:217], v[52:67]
	s_waitcnt vmcnt(7)
	ds_write_b128 v167, v[68:71] offset:18432
	v_mfma_f32_32x32x16_bf16 v[36:51], v[202:205], v[178:181], v[36:51]
	s_waitcnt vmcnt(6)
	ds_write_b128 v167, v[72:75] offset:55296
	v_mfma_f32_32x32x16_bf16 v[20:35], v[174:177], v[214:217], v[20:35]
	s_waitcnt vmcnt(5)
	ds_write_b128 v190, v[76:79] offset:18432
	v_mfma_f32_32x32x16_bf16 v[4:19], v[174:177], v[178:181], v[4:19]
	s_waitcnt vmcnt(4)
	ds_write_b128 v190, v[80:83] offset:55296
	s_waitcnt lgkmcnt(4)
	v_mfma_f32_32x32x16_bf16 v[52:67], v[206:209], v[218:221], v[52:67]
	s_waitcnt vmcnt(3)
	ds_write_b128 v191, v[84:87] offset:18432
	v_mfma_f32_32x32x16_bf16 v[36:51], v[206:209], v[222:225], v[36:51]
	s_waitcnt vmcnt(2)
	ds_write_b128 v191, v[92:95] offset:55296
	v_mfma_f32_32x32x16_bf16 v[20:35], v[210:213], v[218:221], v[20:35]
	s_waitcnt vmcnt(1)
	ds_write_b128 v192, v[104:107] offset:18432
	v_mfma_f32_32x32x16_bf16 v[4:19], v[210:213], v[222:225], v[4:19]
	s_waitcnt vmcnt(0)
	ds_write_b128 v192, v[112:115] offset:55296
	s_waitcnt lgkmcnt(0)
	s_barrier
	ds_read_b128 v[174:177], v196
	ds_read_b128 v[178:181], v196 offset:32
	ds_read_b128 v[202:205], v196 offset:4608
	ds_read_b128 v[206:209], v196 offset:4640
	ds_read_b128 v[210:213], v197 offset:36864
	ds_read_b128 v[214:217], v197 offset:36896
	ds_read_b128 v[218:221], v197 offset:41472
	ds_read_b128 v[222:225], v197 offset:41504
	s_waitcnt lgkmcnt(3)
	v_mfma_f32_32x32x16_bf16 v[52:67], v[174:177], v[210:213], v[52:67]
	s_waitcnt lgkmcnt(1)
	v_mfma_f32_32x32x16_bf16 v[36:51], v[174:177], v[218:221], v[36:51]
	v_mfma_f32_32x32x16_bf16 v[4:19], v[202:205], v[218:221], v[4:19]
	s_waitcnt lgkmcnt(0)
	v_mfma_f32_32x32x16_bf16 v[36:51], v[178:181], v[222:225], v[36:51]
	v_mfma_f32_32x32x16_bf16 v[4:19], v[206:209], v[222:225], v[4:19]
	ds_read_b128 v[222:225], v197 offset:41568
	ds_read_b128 v[174:177], v196 offset:4672
	v_mfma_f32_32x32x16_bf16 v[20:35], v[202:205], v[210:213], v[20:35]
	ds_read_b128 v[210:213], v196 offset:4704
	ds_read_b128 v[202:205], v196 offset:64
	v_mfma_f32_32x32x16_bf16 v[52:67], v[178:181], v[214:217], v[52:67]
	ds_read_b128 v[218:221], v197 offset:36960
	ds_read_b128 v[178:181], v197 offset:41536
	v_mfma_f32_32x32x16_bf16 v[20:35], v[206:209], v[214:217], v[20:35]
	ds_read_b128 v[214:217], v197 offset:36928
	ds_read_b128 v[206:209], v196 offset:96
	s_waitcnt lgkmcnt(1)
	v_mfma_f32_32x32x16_bf16 v[52:67], v[202:205], v[214:217], v[52:67]
	v_mfma_f32_32x32x16_bf16 v[36:51], v[202:205], v[178:181], v[36:51]
	v_mfma_f32_32x32x16_bf16 v[20:35], v[174:177], v[214:217], v[20:35]
	v_mfma_f32_32x32x16_bf16 v[4:19], v[174:177], v[178:181], v[4:19]
	s_waitcnt lgkmcnt(0)
	v_mfma_f32_32x32x16_bf16 v[52:67], v[206:209], v[218:221], v[52:67]
	v_mfma_f32_32x32x16_bf16 v[36:51], v[206:209], v[222:225], v[36:51]
	v_mfma_f32_32x32x16_bf16 v[20:35], v[210:213], v[218:221], v[20:35]
	v_mfma_f32_32x32x16_bf16 v[4:19], v[210:213], v[222:225], v[4:19]
	s_waitcnt lgkmcnt(0)
	s_barrier
	s_nop 7
	s_nop 3
	s_branch .LBB0_53

; DI int get_tid() { int t = (int)__builtin_amdgcn_workitem_id_x(); asm volatile("" : "+v"(t)); return t; }
;     ...
;         for (;;) {
;             __syncthreads();
;             if (get_tid() == 0) st[2] = sub ? 0xffffffffu : atomicAdd(ctr, 1u);
;             __syncthreads();
;             const int it = (int)st[2];
;             if (it < 0 || it >= n5) break;
;             if (it < n1) hyena_lat_item(p, layer, it, smem);
;             else if (it < n2) { const int j = it - n1, bh = j >> 5, qt = j & 31; attn_item(p, (const bf16_t*)(p.ws + WS_Q) + (size_t)bh * SEQ * 96, bh, qt * 128, NKEY, (bh / 6) * SEQ, smem); }
.LBB0_307:
	s_or_b64 exec, exec, s[10:11]
	s_waitcnt vmcnt(0)
	v_readfirstlane_b32 s8, v1
	s_nop 1
	s_cmp_lt_u32 s8, 0x500
	s_cbranch_scc0 .Lp6ord_done
	s_cmp_lt_u32 s8, 0x200
	s_cbranch_scc0 .Lp6ord_b
	s_add_u32 s8, s8, 0x200
	s_branch .Lp6ord_done
.Lp6ord_b:
	s_cmp_lt_u32 s8, 0x400
	s_cbranch_scc0 .Lp6ord_c
	s_sub_u32 s9, s8, 0x200
	s_and_b32 s12, s9, 1
	s_lshr_b32 s9, s9, 1
	s_cmp_eq_u32 s12, 0
	s_cselect_b32 s12, 0x400, 0
	s_add_u32 s8, s9, s12
	s_branch .Lp6ord_done
.Lp6ord_c:
	s_sub_u32 s8, s8, 0x300
.Lp6ord_done:
	s_sub_u32 s9, s8, 0x200
	s_cmp_lt_u32 s9, 0x300
	s_cbranch_scc0 .Lattn_xcd_done
	s_getreg_b32 s9, hwreg(HW_REG_XCC_ID, 0, 4)
	s_and_b32 s9, s9, 7
	s_mov_b32 s12, 0

; template <class Epi, class ColV>
; DI void gemm_tile(const bf16_t* __restrict__ A, int lda, const bf16_t* __restrict__ Bt, int ldb, int K, int m0, int n0, unsigned char* smem, Epi epi, ColV colv, const bf16_t* __restrict__ HYT = nullptr) {
;     ...
;     auto step = [&](int kt, u32x4 (&ldset)[8], const u32x4 (&stset)[8]) {
;         const int buf = kt & 1;
;         if (kt + 2 < nk) gload(ldset, kt + 2);
;         const bf16_t* Ab = As + (buf * 128 + 64 * wr + li) * LS + 8 * lh;
;         const bf16_t* Bb = Bs + (buf * 128 + 64 * wc + li) * LS + 8 * lh;
;         bf16x8 fa[2][2], fb[2][2], ga[2][2], gb[2][2];
; #pragma unroll
;         for (int k2 = 0; k2 < 2; ++k2) { fa[k2][0] = ld8(Ab + 16 * k2); fa[k2][1] = ld8(Ab + 32 * LS + 16 * k2); fb[k2][0] = ld8(Bb + 16 * k2); fb[k2][1] = ld8(Bb + 32 * LS + 16 * k2); }
;         __builtin_amdgcn_sched_barrier(0);
; #pragma unroll
;         for (int k2 = 0; k2 < 2; ++k2) {
;             acc[0][0] = MFMA(fa[k2][0], fb[k2][0], acc[0][0]); acc[0][1] = MFMA(fa[k2][0], fb[k2][1], acc[0][1]);
;             acc[1][0] = MFMA(fa[k2][1], fb[k2][0], acc[1][0]); acc[1][1] = MFMA(fa[k2][1], fb[k2][1], acc[1][1]);
;         }
; #pragma unroll
;         for (int k2 = 0; k2 < 2; ++k2) { const int ks = 2 + k2; ga[k2][0] = ld8(Ab + 16 * ks); ga[k2][1] = ld8(Ab + 32 * LS + 16 * ks); gb[k2][0] = ld8(Bb + 16 * ks); gb[k2][1] = ld8(Bb + 32 * LS + 16 * ks); }
; #pragma unroll
;         for (int k2 = 0; k2 < 2; ++k2) {
;             acc[0][0] = MFMA(ga[k2][0], gb[k2][0], acc[0][0]); acc[0][1] = MFMA(ga[k2][0], gb[k2][1], acc[0][1]);
;             acc[1][0] = MFMA(ga[k2][1], gb[k2][0], acc[1][0]); acc[1][1] = MFMA(ga[k2][1], gb[k2][1], acc[1][1]);
;         }
;         if (kt + 1 < nk) sstore(stset, buf ^ 1, kt + 1);
; #pragma unroll
;         for (int i = 0; i < 8; ++i) { __builtin_amdgcn_sched_group_barrier(0x008, 1, 0); __builtin_amdgcn_sched_group_barrier(0x100, 1, 0); }
; #pragma unroll
;         for (int i = 0; i < 8; ++i) { __builtin_amdgcn_sched_group_barrier(0x008, 1, 0); __builtin_amdgcn_sched_group_barrier(0x200, 1, 0); }
;         __builtin_amdgcn_sched_barrier(0);
;         __syncthreads();
;     };
;     gload(R0, 0); gload(R1, 1);
;     sstore(R0, 0, 0); __syncthreads();
;     for (int kt = 0; kt < nk; kt += 2) {
;         step(kt, R0, R1);
;         if (kt + 1 < nk) step(kt + 1, R1, R0);
;     }
.LBB0_1558:
	s_cmp_lt_u32 s19, 14
	s_cselect_b64 s[12:13], -1, 0
	s_cmp_gt_u32 s19, 13
	s_cselect_b64 s[10:11], -1, 0
	s_and_b64 vcc, exec, s[10:11]
	v_lshl_add_u64 v[164:165], v[144:145], 0, v[2:3]
	v_lshl_add_u64 v[162:163], v[0:1], 0, v[2:3]
	v_lshl_add_u64 v[160:161], v[142:143], 0, v[2:3]
	v_lshl_add_u64 v[158:159], v[132:133], 0, v[2:3]
	v_lshl_add_u64 v[156:157], v[140:141], 0, v[2:3]
	v_lshl_add_u64 v[154:155], v[134:135], 0, v[2:3]
	v_lshl_add_u64 v[152:153], v[138:139], 0, v[2:3]
	v_lshl_add_u64 v[146:147], v[136:137], 0, v[2:3]
	s_mov_b32 s100, 0x26ca000
	s_mov_b32 s101, 0
	v_lshl_add_u64 v[164:165], v[164:165], 0, s[100:101]
	v_lshl_add_u64 v[160:161], v[160:161], 0, s[100:101]
	v_lshl_add_u64 v[156:157], v[156:157], 0, s[100:101]
	v_lshl_add_u64 v[152:153], v[152:153], 0, s[100:101]
	global_load_dwordx4 v[132:135], v[164:165], off offset:256
	global_load_dwordx4 v[136:139], v[162:163], off offset:256
	global_load_dwordx4 v[140:143], v[160:161], off offset:256
	global_load_dwordx4 v[198:201], v[158:159], off offset:256
	global_load_dwordx4 v[174:177], v[156:157], off offset:256
	global_load_dwordx4 v[178:181], v[154:155], off offset:256
	global_load_dwordx4 v[242:245], v[152:153], off offset:256
	global_load_dwordx4 v[246:249], v[146:147], off offset:256
	global_load_dwordx4 v[68:71], v[164:165], off offset:384
	global_load_dwordx4 v[72:75], v[162:163], off offset:384
	global_load_dwordx4 v[76:79], v[160:161], off offset:384
	global_load_dwordx4 v[80:83], v[158:159], off offset:384
	global_load_dwordx4 v[84:87], v[156:157], off offset:384
	global_load_dwordx4 v[88:91], v[154:155], off offset:384
	global_load_dwordx4 v[92:95], v[152:153], off offset:384
	global_load_dwordx4 v[104:107], v[146:147], off offset:384
	ds_read_b128 v[202:205], v194
	ds_read_b128 v[206:209], v194 offset:32
	ds_read_b128 v[210:213], v194 offset:4608
	ds_read_b128 v[214:217], v194 offset:4640
	ds_read_b128 v[218:221], v195 offset:36864
	ds_read_b128 v[222:225], v195 offset:36896
	ds_read_b128 v[226:229], v195 offset:41472
	ds_read_b128 v[230:233], v195 offset:41504
	s_waitcnt lgkmcnt(3)
	v_mfma_f32_32x32x16_bf16 v[52:67], v[202:205], v[218:221], v[52:67]
	s_waitcnt lgkmcnt(1)
	v_mfma_f32_32x32x16_bf16 v[36:51], v[202:205], v[226:229], v[36:51]
	v_mfma_f32_32x32x16_bf16 v[4:19], v[210:213], v[226:229], v[4:19]
	s_waitcnt lgkmcnt(0)
	v_mfma_f32_32x32x16_bf16 v[36:51], v[206:209], v[230:233], v[36:51]
	v_mfma_f32_32x32x16_bf16 v[4:19], v[214:217], v[230:233], v[4:19]
	ds_read_b128 v[230:233], v195 offset:41568
	ds_read_b128 v[202:205], v194 offset:4672
	v_mfma_f32_32x32x16_bf16 v[20:35], v[210:213], v[218:221], v[20:35]
	ds_read_b128 v[218:221], v194 offset:4704
	ds_read_b128 v[210:213], v194 offset:64
	v_mfma_f32_32x32x16_bf16 v[52:67], v[206:209], v[222:225], v[52:67]
	ds_read_b128 v[226:229], v195 offset:36960
	ds_read_b128 v[206:209], v195 offset:41536
	v_mfma_f32_32x32x16_bf16 v[20:35], v[214:217], v[222:225], v[20:35]
	ds_read_b128 v[222:225], v195 offset:36928
	ds_read_b128 v[214:217], v194 offset:96
	s_waitcnt lgkmcnt(1)
	v_mfma_f32_32x32x16_bf16 v[52:67], v[210:213], v[222:225], v[52:67]
	s_waitcnt vmcnt(16)
	ds_write_b128 v167, v[96:99] offset:18432
	v_mfma_f32_32x32x16_bf16 v[36:51], v[210:213], v[206:209], v[36:51]
	ds_write_b128 v167, v[100:103] offset:55296
	v_mfma_f32_32x32x16_bf16 v[20:35], v[202:205], v[222:225], v[20:35]
	ds_write_b128 v190, v[108:111] offset:18432
	v_mfma_f32_32x32x16_bf16 v[4:19], v[202:205], v[206:209], v[4:19]
	ds_write_b128 v190, v[112:115] offset:55296
	s_waitcnt lgkmcnt(4)
	v_mfma_f32_32x32x16_bf16 v[52:67], v[214:217], v[226:229], v[52:67]
	ds_write_b128 v191, v[116:119] offset:18432
	v_mfma_f32_32x32x16_bf16 v[36:51], v[214:217], v[230:233], v[36:51]
	ds_write_b128 v191, v[120:123] offset:55296
	v_mfma_f32_32x32x16_bf16 v[20:35], v[218:221], v[226:229], v[20:35]
	ds_write_b128 v192, v[124:127] offset:18432
	v_mfma_f32_32x32x16_bf16 v[4:19], v[218:221], v[230:233], v[4:19]
	ds_write_b128 v192, v[128:131] offset:55296
	s_waitcnt lgkmcnt(0)
	s_barrier
	global_load_dwordx4 v[96:99], v[164:165], off offset:512
	global_load_dwordx4 v[100:103], v[162:163], off offset:512
	global_load_dwordx4 v[108:111], v[160:161], off offset:512
	global_load_dwordx4 v[112:115], v[158:159], off offset:512
	global_load_dwordx4 v[116:119], v[156:157], off offset:512
	global_load_dwordx4 v[120:123], v[154:155], off offset:512
	global_load_dwordx4 v[124:127], v[152:153], off offset:512
	global_load_dwordx4 v[128:131], v[146:147], off offset:512
	ds_read_b128 v[202:205], v196
	ds_read_b128 v[206:209], v196 offset:32
	ds_read_b128 v[210:213], v196 offset:4608
	ds_read_b128 v[214:217], v196 offset:4640
	ds_read_b128 v[218:221], v197 offset:36864
	ds_read_b128 v[222:225], v197 offset:36896
	ds_read_b128 v[226:229], v197 offset:41472
	ds_read_b128 v[230:233], v197 offset:41504
	s_waitcnt lgkmcnt(3)
	v_mfma_f32_32x32x16_bf16 v[52:67], v[202:205], v[218:221], v[52:67]
	s_waitcnt lgkmcnt(1)
	v_mfma_f32_32x32x16_bf16 v[36:51], v[202:205], v[226:229], v[36:51]
	v_mfma_f32_32x32x16_bf16 v[4:19], v[210:213], v[226:229], v[4:19]
	s_waitcnt lgkmcnt(0)
	v_mfma_f32_32x32x16_bf16 v[36:51], v[206:209], v[230:233], v[36:51]
	v_mfma_f32_32x32x16_bf16 v[4:19], v[214:217], v[230:233], v[4:19]
	ds_read_b128 v[230:233], v197 offset:41568
	ds_read_b128 v[202:205], v196 offset:4672
	v_mfma_f32_32x32x16_bf16 v[20:35], v[210:213], v[218:221], v[20:35]
	ds_read_b128 v[218:221], v196 offset:4704
	ds_read_b128 v[210:213], v196 offset:64
	v_mfma_f32_32x32x16_bf16 v[52:67], v[206:209], v[222:225], v[52:67]
	ds_read_b128 v[226:229], v197 offset:36960
	ds_read_b128 v[206:209], v197 offset:41536
	v_mfma_f32_32x32x16_bf16 v[20:35], v[214:217], v[222:225], v[20:35]
	ds_read_b128 v[222:225], v197 offset:36928
	ds_read_b128 v[214:217], v196 offset:96
	s_waitcnt lgkmcnt(1)
	v_mfma_f32_32x32x16_bf16 v[52:67], v[210:213], v[222:225], v[52:67]
	s_waitcnt vmcnt(23)
	ds_write_b128 v167, v[132:135]
	v_mfma_f32_32x32x16_bf16 v[36:51], v[210:213], v[206:209], v[36:51]
	s_waitcnt vmcnt(22)
	ds_write_b128 v167, v[136:139] offset:36864
	v_mfma_f32_32x32x16_bf16 v[20:35], v[202:205], v[222:225], v[20:35]
	s_waitcnt vmcnt(21)
	ds_write_b128 v190, v[140:143]
	v_mfma_f32_32x32x16_bf16 v[4:19], v[202:205], v[206:209], v[4:19]
	s_waitcnt vmcnt(20)
	ds_write_b128 v190, v[198:201] offset:36864
	s_waitcnt lgkmcnt(4)
	v_mfma_f32_32x32x16_bf16 v[52:67], v[214:217], v[226:229], v[52:67]
	s_waitcnt vmcnt(19)
	ds_write_b128 v191, v[174:177]
	v_mfma_f32_32x32x16_bf16 v[36:51], v[214:217], v[230:233], v[36:51]
	s_waitcnt vmcnt(18)
	ds_write_b128 v191, v[178:181] offset:36864
	v_mfma_f32_32x32x16_bf16 v[20:35], v[218:221], v[226:229], v[20:35]
	s_waitcnt vmcnt(17)
	ds_write_b128 v192, v[242:245]
	v_mfma_f32_32x32x16_bf16 v[4:19], v[218:221], v[230:233], v[4:19]
	s_waitcnt vmcnt(16)
	ds_write_b128 v192, v[246:249] offset:36864
	s_waitcnt lgkmcnt(0)
	s_barrier
; #define MFMA(a, b, c) __builtin_amdgcn_mfma_f32_32x32x16_bf16((a), (b), (c), 0, 0, 0)
; template <class Epi, class ColV>
; DI void gemm_tile(const bf16_t* __restrict__ A, int lda, const bf16_t* __restrict__ Bt, int ldb, int K, int m0, int n0, unsigned char* smem, Epi epi, ColV colv, const bf16_t* __restrict__ HYT = nullptr) {
;     ...
;     auto step = [&](int kt, u32x4 (&ldset)[8], const u32x4 (&stset)[8]) {
;         const int buf = kt & 1;
;         if (kt + 2 < nk) gload(ldset, kt + 2);
;         const bf16_t* Ab = As + (buf * 128 + 64 * wr + li) * LS + 8 * lh;
;         const bf16_t* Bb = Bs + (buf * 128 + 64 * wc + li) * LS + 8 * lh;
;         bf16x8 fa[2][2], fb[2][2], ga[2][2], gb[2][2];
; #pragma unroll
;         for (int k2 = 0; k2 < 2; ++k2) { fa[k2][0] = ld8(Ab + 16 * k2); fa[k2][1] = ld8(Ab + 32 * LS + 16 * k2); fb[k2][0] = ld8(Bb + 16 * k2); fb[k2][1] = ld8(Bb + 32 * LS + 16 * k2); }
;         __builtin_amdgcn_sched_barrier(0);
; #pragma unroll
;         for (int k2 = 0; k2 < 2; ++k2) {
;             acc[0][0] = MFMA(fa[k2][0], fb[k2][0], acc[0][0]); acc[0][1] = MFMA(fa[k2][0], fb[k2][1], acc[0][1]);
;             acc[1][0] = MFMA(fa[k2][1], fb[k2][0], acc[1][0]); acc[1][1] = MFMA(fa[k2][1], fb[k2][1], acc[1][1]);
;         }
; #pragma unroll
;         for (int k2 = 0; k2 < 2; ++k2) { const int ks = 2 + k2; ga[k2][0] = ld8(Ab + 16 * ks); ga[k2][1] = ld8(Ab + 32 * LS + 16 * ks); gb[k2][0] = ld8(Bb + 16 * ks); gb[k2][1] = ld8(Bb + 32 * LS + 16 * ks); }
; #pragma unroll
;         for (int k2 = 0; k2 < 2; ++k2) {
;             acc[0][0] = MFMA(ga[k2][0], gb[k2][0], acc[0][0]); acc[0][1] = MFMA(ga[k2][0], gb[k2][1], acc[0][1]);
;             acc[1][0] = MFMA(ga[k2][1], gb[k2][0], acc[1][0]); acc[1][1] = MFMA(ga[k2][1], gb[k2][1], acc[1][1]);
;         }
;         if (kt + 1 < nk) sstore(stset, buf ^ 1, kt + 1);
; #pragma unroll
;         for (int i = 0; i < 8; ++i) { __builtin_amdgcn_sched_group_barrier(0x008, 1, 0); __builtin_amdgcn_sched_group_barrier(0x100, 1, 0); }
; #pragma unroll
;         for (int i = 0; i < 8; ++i) { __builtin_amdgcn_sched_group_barrier(0x008, 1, 0); __builtin_amdgcn_sched_group_barrier(0x200, 1, 0); }
;         __builtin_amdgcn_sched_barrier(0);
;         __syncthreads();
	global_load_dwordx4 v[132:135], v[164:165], off offset:640
	global_load_dwordx4 v[136:139], v[162:163], off offset:640
	global_load_dwordx4 v[140:143], v[160:161], off offset:640
	global_load_dwordx4 v[198:201], v[158:159], off offset:640
	global_load_dwordx4 v[174:177], v[156:157], off offset:640
	global_load_dwordx4 v[178:181], v[154:155], off offset:640
	global_load_dwordx4 v[242:245], v[152:153], off offset:640
	global_load_dwordx4 v[246:249], v[146:147], off offset:640
	ds_read_b128 v[202:205], v194
	ds_read_b128 v[206:209], v194 offset:32
	ds_read_b128 v[210:213], v194 offset:4608
	ds_read_b128 v[214:217], v194 offset:4640
	ds_read_b128 v[218:221], v195 offset:36864
	ds_read_b128 v[222:225], v195 offset:36896
	ds_read_b128 v[226:229], v195 offset:41472
	ds_read_b128 v[230:233], v195 offset:41504
	s_waitcnt lgkmcnt(3)
	v_mfma_f32_32x32x16_bf16 v[52:67], v[202:205], v[218:221], v[52:67]
	s_waitcnt lgkmcnt(1)
	v_mfma_f32_32x32x16_bf16 v[36:51], v[202:205], v[226:229], v[36:51]
	v_mfma_f32_32x32x16_bf16 v[4:19], v[210:213], v[226:229], v[4:19]
	s_waitcnt lgkmcnt(0)
	v_mfma_f32_32x32x16_bf16 v[36:51], v[206:209], v[230:233], v[36:51]
	v_mfma_f32_32x32x16_bf16 v[4:19], v[214:217], v[230:233], v[4:19]
	ds_read_b128 v[230:233], v195 offset:41568
	ds_read_b128 v[202:205], v194 offset:4672
	v_mfma_f32_32x32x16_bf16 v[20:35], v[210:213], v[218:221], v[20:35]
	ds_read_b128 v[218:221], v194 offset:4704
	ds_read_b128 v[210:213], v194 offset:64
	v_mfma_f32_32x32x16_bf16 v[52:67], v[206:209], v[222:225], v[52:67]
	ds_read_b128 v[226:229], v195 offset:36960
	ds_read_b128 v[206:209], v195 offset:41536
	v_mfma_f32_32x32x16_bf16 v[20:35], v[214:217], v[222:225], v[20:35]
	ds_read_b128 v[222:225], v195 offset:36928
	ds_read_b128 v[214:217], v194 offset:96
	s_waitcnt lgkmcnt(1)
	v_mfma_f32_32x32x16_bf16 v[52:67], v[210:213], v[222:225], v[52:67]
	s_waitcnt vmcnt(23)
	ds_write_b128 v167, v[68:71] offset:18432
	v_mfma_f32_32x32x16_bf16 v[36:51], v[210:213], v[206:209], v[36:51]
	s_waitcnt vmcnt(22)
	ds_write_b128 v167, v[72:75] offset:55296
	v_mfma_f32_32x32x16_bf16 v[20:35], v[202:205], v[222:225], v[20:35]
	s_waitcnt vmcnt(21)
	ds_write_b128 v190, v[76:79] offset:18432
	v_mfma_f32_32x32x16_bf16 v[4:19], v[202:205], v[206:209], v[4:19]
	s_waitcnt vmcnt(20)
	ds_write_b128 v190, v[80:83] offset:55296
	s_waitcnt lgkmcnt(4)
	v_mfma_f32_32x32x16_bf16 v[52:67], v[214:217], v[226:229], v[52:67]
	s_waitcnt vmcnt(19)
	ds_write_b128 v191, v[84:87] offset:18432
	v_mfma_f32_32x32x16_bf16 v[36:51], v[214:217], v[230:233], v[36:51]
	s_waitcnt vmcnt(18)
	ds_write_b128 v191, v[88:91] offset:55296
	v_mfma_f32_32x32x16_bf16 v[20:35], v[218:221], v[226:229], v[20:35]
	s_waitcnt vmcnt(17)
	ds_write_b128 v192, v[92:95] offset:18432
	v_mfma_f32_32x32x16_bf16 v[4:19], v[218:221], v[230:233], v[4:19]
	s_waitcnt vmcnt(16)
	ds_write_b128 v192, v[104:107] offset:55296
	s_waitcnt lgkmcnt(0)
	s_barrier
	global_load_dwordx4 v[68:71], v[164:165], off offset:768
	global_load_dwordx4 v[72:75], v[162:163], off offset:768
	global_load_dwordx4 v[76:79], v[160:161], off offset:768
	global_load_dwordx4 v[80:83], v[158:159], off offset:768
	global_load_dwordx4 v[84:87], v[156:157], off offset:768
	global_load_dwordx4 v[88:91], v[154:155], off offset:768
	global_load_dwordx4 v[92:95], v[152:153], off offset:768
	global_load_dwordx4 v[104:107], v[146:147], off offset:768
	ds_read_b128 v[202:205], v196
	ds_read_b128 v[206:209], v196 offset:32
	ds_read_b128 v[210:213], v196 offset:4608
	ds_read_b128 v[214:217], v196 offset:4640
	ds_read_b128 v[218:221], v197 offset:36864
	ds_read_b128 v[222:225], v197 offset:36896
	ds_read_b128 v[226:229], v197 offset:41472
	ds_read_b128 v[230:233], v197 offset:41504
	s_waitcnt lgkmcnt(3)
	v_mfma_f32_32x32x16_bf16 v[52:67], v[202:205], v[218:221], v[52:67]
	s_waitcnt lgkmcnt(1)
	v_mfma_f32_32x32x16_bf16 v[36:51], v[202:205], v[226:229], v[36:51]
	v_mfma_f32_32x32x16_bf16 v[4:19], v[210:213], v[226:229], v[4:19]
	s_waitcnt lgkmcnt(0)
	v_mfma_f32_32x32x16_bf16 v[36:51], v[206:209], v[230:233], v[36:51]
	v_mfma_f32_32x32x16_bf16 v[4:19], v[214:217], v[230:233], v[4:19]
	ds_read_b128 v[230:233], v197 offset:41568
	ds_read_b128 v[202:205], v196 offset:4672
	v_mfma_f32_32x32x16_bf16 v[20:35], v[210:213], v[218:221], v[20:35]
	ds_read_b128 v[218:221], v196 offset:4704
	ds_read_b128 v[210:213], v196 offset:64
	v_mfma_f32_32x32x16_bf16 v[52:67], v[206:209], v[222:225], v[52:67]
	ds_read_b128 v[226:229], v197 offset:36960
	ds_read_b128 v[206:209], v197 offset:41536
	v_mfma_f32_32x32x16_bf16 v[20:35], v[214:217], v[222:225], v[20:35]
	ds_read_b128 v[222:225], v197 offset:36928
	ds_read_b128 v[214:217], v196 offset:96
	s_waitcnt lgkmcnt(1)
	v_mfma_f32_32x32x16_bf16 v[52:67], v[210:213], v[222:225], v[52:67]
	s_waitcnt vmcnt(23)
	ds_write_b128 v167, v[96:99]
	v_mfma_f32_32x32x16_bf16 v[36:51], v[210:213], v[206:209], v[36:51]
	s_waitcnt vmcnt(22)
	ds_write_b128 v167, v[100:103] offset:36864
	v_mfma_f32_32x32x16_bf16 v[20:35], v[202:205], v[222:225], v[20:35]
	s_waitcnt vmcnt(21)
	ds_write_b128 v190, v[108:111]
	v_mfma_f32_32x32x16_bf16 v[4:19], v[202:205], v[206:209], v[4:19]
	s_waitcnt vmcnt(20)
	ds_write_b128 v190, v[112:115] offset:36864
	s_waitcnt lgkmcnt(4)
	v_mfma_f32_32x32x16_bf16 v[52:67], v[214:217], v[226:229], v[52:67]
	s_waitcnt vmcnt(19)
	ds_write_b128 v191, v[116:119]
	v_mfma_f32_32x32x16_bf16 v[36:51], v[214:217], v[230:233], v[36:51]
	s_waitcnt vmcnt(18)
	ds_write_b128 v191, v[120:123] offset:36864
	v_mfma_f32_32x32x16_bf16 v[20:35], v[218:221], v[226:229], v[20:35]
	s_waitcnt vmcnt(17)
	ds_write_b128 v192, v[124:127]
	v_mfma_f32_32x32x16_bf16 v[4:19], v[218:221], v[230:233], v[4:19]
	s_waitcnt vmcnt(16)
	ds_write_b128 v192, v[128:131] offset:36864
	s_waitcnt lgkmcnt(0)
	s_barrier
; #define MFMA(a, b, c) __builtin_amdgcn_mfma_f32_32x32x16_bf16((a), (b), (c), 0, 0, 0)
; template <class Epi, class ColV>
; DI void gemm_tile(const bf16_t* __restrict__ A, int lda, const bf16_t* __restrict__ Bt, int ldb, int K, int m0, int n0, unsigned char* smem, Epi epi, ColV colv, const bf16_t* __restrict__ HYT = nullptr) {
;     ...
;     auto step = [&](int kt, u32x4 (&ldset)[8], const u32x4 (&stset)[8]) {
;         const int buf = kt & 1;
;         if (kt + 2 < nk) gload(ldset, kt + 2);
;         const bf16_t* Ab = As + (buf * 128 + 64 * wr + li) * LS + 8 * lh;
;         const bf16_t* Bb = Bs + (buf * 128 + 64 * wc + li) * LS + 8 * lh;
;         bf16x8 fa[2][2], fb[2][2], ga[2][2], gb[2][2];
; #pragma unroll
;         for (int k2 = 0; k2 < 2; ++k2) { fa[k2][0] = ld8(Ab + 16 * k2); fa[k2][1] = ld8(Ab + 32 * LS + 16 * k2); fb[k2][0] = ld8(Bb + 16 * k2); fb[k2][1] = ld8(Bb + 32 * LS + 16 * k2); }
;         __builtin_amdgcn_sched_barrier(0);
; #pragma unroll
;         for (int k2 = 0; k2 < 2; ++k2) {
;             acc[0][0] = MFMA(fa[k2][0], fb[k2][0], acc[0][0]); acc[0][1] = MFMA(fa[k2][0], fb[k2][1], acc[0][1]);
;             acc[1][0] = MFMA(fa[k2][1], fb[k2][0], acc[1][0]); acc[1][1] = MFMA(fa[k2][1], fb[k2][1], acc[1][1]);
;         }
; #pragma unroll
;         for (int k2 = 0; k2 < 2; ++k2) { const int ks = 2 + k2; ga[k2][0] = ld8(Ab + 16 * ks); ga[k2][1] = ld8(Ab + 32 * LS + 16 * ks); gb[k2][0] = ld8(Bb + 16 * ks); gb[k2][1] = ld8(Bb + 32 * LS + 16 * ks); }
; #pragma unroll
;         for (int k2 = 0; k2 < 2; ++k2) {
;             acc[0][0] = MFMA(ga[k2][0], gb[k2][0], acc[0][0]); acc[0][1] = MFMA(ga[k2][0], gb[k2][1], acc[0][1]);
;             acc[1][0] = MFMA(ga[k2][1], gb[k2][0], acc[1][0]); acc[1][1] = MFMA(ga[k2][1], gb[k2][1], acc[1][1]);
;         }
;         if (kt + 1 < nk) sstore(stset, buf ^ 1, kt + 1);
; #pragma unroll
;         for (int i = 0; i < 8; ++i) { __builtin_amdgcn_sched_group_barrier(0x008, 1, 0); __builtin_amdgcn_sched_group_barrier(0x100, 1, 0); }
; #pragma unroll
;         for (int i = 0; i < 8; ++i) { __builtin_amdgcn_sched_group_barrier(0x008, 1, 0); __builtin_amdgcn_sched_group_barrier(0x200, 1, 0); }
;         __builtin_amdgcn_sched_barrier(0);
;         __syncthreads();
	global_load_dwordx4 v[96:99], v[164:165], off offset:896
	global_load_dwordx4 v[100:103], v[162:163], off offset:896
	global_load_dwordx4 v[108:111], v[160:161], off offset:896
	global_load_dwordx4 v[112:115], v[158:159], off offset:896
	global_load_dwordx4 v[116:119], v[156:157], off offset:896
	global_load_dwordx4 v[120:123], v[154:155], off offset:896
	global_load_dwordx4 v[124:127], v[152:153], off offset:896
	global_load_dwordx4 v[128:131], v[146:147], off offset:896
	ds_read_b128 v[202:205], v194
	ds_read_b128 v[206:209], v194 offset:32
	ds_read_b128 v[210:213], v194 offset:4608
	ds_read_b128 v[214:217], v194 offset:4640
	ds_read_b128 v[218:221], v195 offset:36864
	ds_read_b128 v[222:225], v195 offset:36896
	ds_read_b128 v[226:229], v195 offset:41472
	ds_read_b128 v[230:233], v195 offset:41504
	s_waitcnt lgkmcnt(3)
	v_mfma_f32_32x32x16_bf16 v[52:67], v[202:205], v[218:221], v[52:67]
	s_waitcnt lgkmcnt(1)
	v_mfma_f32_32x32x16_bf16 v[36:51], v[202:205], v[226:229], v[36:51]
	v_mfma_f32_32x32x16_bf16 v[4:19], v[210:213], v[226:229], v[4:19]
	s_waitcnt lgkmcnt(0)
	v_mfma_f32_32x32x16_bf16 v[36:51], v[206:209], v[230:233], v[36:51]
	v_mfma_f32_32x32x16_bf16 v[4:19], v[214:217], v[230:233], v[4:19]
	ds_read_b128 v[230:233], v195 offset:41568
	ds_read_b128 v[202:205], v194 offset:4672
	v_mfma_f32_32x32x16_bf16 v[20:35], v[210:213], v[218:221], v[20:35]
	ds_read_b128 v[218:221], v194 offset:4704
	ds_read_b128 v[210:213], v194 offset:64
	v_mfma_f32_32x32x16_bf16 v[52:67], v[206:209], v[222:225], v[52:67]
	ds_read_b128 v[226:229], v195 offset:36960
	ds_read_b128 v[206:209], v195 offset:41536
	v_mfma_f32_32x32x16_bf16 v[20:35], v[214:217], v[222:225], v[20:35]
	ds_read_b128 v[222:225], v195 offset:36928
	ds_read_b128 v[214:217], v194 offset:96
	s_waitcnt lgkmcnt(1)
	v_mfma_f32_32x32x16_bf16 v[52:67], v[210:213], v[222:225], v[52:67]
	s_waitcnt vmcnt(23)
	ds_write_b128 v167, v[132:135] offset:18432
	v_mfma_f32_32x32x16_bf16 v[36:51], v[210:213], v[206:209], v[36:51]
	s_waitcnt vmcnt(22)
	ds_write_b128 v167, v[136:139] offset:55296
	v_mfma_f32_32x32x16_bf16 v[20:35], v[202:205], v[222:225], v[20:35]
	s_waitcnt vmcnt(21)
	ds_write_b128 v190, v[140:143] offset:18432
	v_mfma_f32_32x32x16_bf16 v[4:19], v[202:205], v[206:209], v[4:19]
	s_waitcnt vmcnt(20)
	ds_write_b128 v190, v[198:201] offset:55296
	s_waitcnt lgkmcnt(4)
	v_mfma_f32_32x32x16_bf16 v[52:67], v[214:217], v[226:229], v[52:67]
	s_waitcnt vmcnt(19)
	ds_write_b128 v191, v[174:177] offset:18432
	v_mfma_f32_32x32x16_bf16 v[36:51], v[214:217], v[230:233], v[36:51]
	s_waitcnt vmcnt(18)
	ds_write_b128 v191, v[178:181] offset:55296
	v_mfma_f32_32x32x16_bf16 v[20:35], v[218:221], v[226:229], v[20:35]
	s_waitcnt vmcnt(17)
	ds_write_b128 v192, v[242:245] offset:18432
	v_mfma_f32_32x32x16_bf16 v[4:19], v[218:221], v[230:233], v[4:19]
	s_waitcnt vmcnt(16)
	ds_write_b128 v192, v[246:249] offset:55296
	s_waitcnt lgkmcnt(0)
	s_barrier
	global_load_dwordx4 v[132:135], v[164:165], off offset:1024
	global_load_dwordx4 v[136:139], v[162:163], off offset:1024
	global_load_dwordx4 v[140:143], v[160:161], off offset:1024
	global_load_dwordx4 v[198:201], v[158:159], off offset:1024
	global_load_dwordx4 v[174:177], v[156:157], off offset:1024
	global_load_dwordx4 v[178:181], v[154:155], off offset:1024
	global_load_dwordx4 v[242:245], v[152:153], off offset:1024
	global_load_dwordx4 v[246:249], v[146:147], off offset:1024
	ds_read_b128 v[202:205], v196
	ds_read_b128 v[206:209], v196 offset:32
	ds_read_b128 v[210:213], v196 offset:4608
	ds_read_b128 v[214:217], v196 offset:4640
	ds_read_b128 v[218:221], v197 offset:36864
	ds_read_b128 v[222:225], v197 offset:36896
	ds_read_b128 v[226:229], v197 offset:41472
	ds_read_b128 v[230:233], v197 offset:41504
	s_waitcnt lgkmcnt(3)
	v_mfma_f32_32x32x16_bf16 v[52:67], v[202:205], v[218:221], v[52:67]
	s_waitcnt lgkmcnt(1)
	v_mfma_f32_32x32x16_bf16 v[36:51], v[202:205], v[226:229], v[36:51]
	v_mfma_f32_32x32x16_bf16 v[4:19], v[210:213], v[226:229], v[4:19]
	s_waitcnt lgkmcnt(0)
	v_mfma_f32_32x32x16_bf16 v[36:51], v[206:209], v[230:233], v[36:51]
	v_mfma_f32_32x32x16_bf16 v[4:19], v[214:217], v[230:233], v[4:19]
	ds_read_b128 v[230:233], v197 offset:41568
	ds_read_b128 v[202:205], v196 offset:4672
	v_mfma_f32_32x32x16_bf16 v[20:35], v[210:213], v[218:221], v[20:35]
	ds_read_b128 v[218:221], v196 offset:4704
	ds_read_b128 v[210:213], v196 offset:64
	v_mfma_f32_32x32x16_bf16 v[52:67], v[206:209], v[222:225], v[52:67]
	ds_read_b128 v[226:229], v197 offset:36960
	ds_read_b128 v[206:209], v197 offset:41536
	v_mfma_f32_32x32x16_bf16 v[20:35], v[214:217], v[222:225], v[20:35]
	ds_read_b128 v[222:225], v197 offset:36928
	ds_read_b128 v[214:217], v196 offset:96
	s_waitcnt lgkmcnt(1)
	v_mfma_f32_32x32x16_bf16 v[52:67], v[210:213], v[222:225], v[52:67]
	s_waitcnt vmcnt(23)
	ds_write_b128 v167, v[68:71]
	v_mfma_f32_32x32x16_bf16 v[36:51], v[210:213], v[206:209], v[36:51]
	s_waitcnt vmcnt(22)
	ds_write_b128 v167, v[72:75] offset:36864
	v_mfma_f32_32x32x16_bf16 v[20:35], v[202:205], v[222:225], v[20:35]
	s_waitcnt vmcnt(21)
	ds_write_b128 v190, v[76:79]
	v_mfma_f32_32x32x16_bf16 v[4:19], v[202:205], v[206:209], v[4:19]
	s_waitcnt vmcnt(20)
	ds_write_b128 v190, v[80:83] offset:36864
	s_waitcnt lgkmcnt(4)
	v_mfma_f32_32x32x16_bf16 v[52:67], v[214:217], v[226:229], v[52:67]
	s_waitcnt vmcnt(19)
	ds_write_b128 v191, v[84:87]
	v_mfma_f32_32x32x16_bf16 v[36:51], v[214:217], v[230:233], v[36:51]
	s_waitcnt vmcnt(18)
	ds_write_b128 v191, v[88:91] offset:36864
	v_mfma_f32_32x32x16_bf16 v[20:35], v[218:221], v[226:229], v[20:35]
	s_waitcnt vmcnt(17)
	ds_write_b128 v192, v[92:95]
	v_mfma_f32_32x32x16_bf16 v[4:19], v[218:221], v[230:233], v[4:19]
	s_waitcnt vmcnt(16)
	ds_write_b128 v192, v[104:107] offset:36864
	s_waitcnt lgkmcnt(0)
	s_barrier
; #define MFMA(a, b, c) __builtin_amdgcn_mfma_f32_32x32x16_bf16((a), (b), (c), 0, 0, 0)
; template <class Epi, class ColV>
; DI void gemm_tile(const bf16_t* __restrict__ A, int lda, const bf16_t* __restrict__ Bt, int ldb, int K, int m0, int n0, unsigned char* smem, Epi epi, ColV colv, const bf16_t* __restrict__ HYT = nullptr) {
;     ...
;     auto step = [&](int kt, u32x4 (&ldset)[8], const u32x4 (&stset)[8]) {
;         const int buf = kt & 1;
;         if (kt + 2 < nk) gload(ldset, kt + 2);
;         const bf16_t* Ab = As + (buf * 128 + 64 * wr + li) * LS + 8 * lh;
;         const bf16_t* Bb = Bs + (buf * 128 + 64 * wc + li) * LS + 8 * lh;
;         bf16x8 fa[2][2], fb[2][2], ga[2][2], gb[2][2];
; #pragma unroll
;         for (int k2 = 0; k2 < 2; ++k2) { fa[k2][0] = ld8(Ab + 16 * k2); fa[k2][1] = ld8(Ab + 32 * LS + 16 * k2); fb[k2][0] = ld8(Bb + 16 * k2); fb[k2][1] = ld8(Bb + 32 * LS + 16 * k2); }
;         __builtin_amdgcn_sched_barrier(0);
; #pragma unroll
;         for (int k2 = 0; k2 < 2; ++k2) {
;             acc[0][0] = MFMA(fa[k2][0], fb[k2][0], acc[0][0]); acc[0][1] = MFMA(fa[k2][0], fb[k2][1], acc[0][1]);
;             acc[1][0] = MFMA(fa[k2][1], fb[k2][0], acc[1][0]); acc[1][1] = MFMA(fa[k2][1], fb[k2][1], acc[1][1]);
;         }
; #pragma unroll
;         for (int k2 = 0; k2 < 2; ++k2) { const int ks = 2 + k2; ga[k2][0] = ld8(Ab + 16 * ks); ga[k2][1] = ld8(Ab + 32 * LS + 16 * ks); gb[k2][0] = ld8(Bb + 16 * ks); gb[k2][1] = ld8(Bb + 32 * LS + 16 * ks); }
; #pragma unroll
;         for (int k2 = 0; k2 < 2; ++k2) {
;             acc[0][0] = MFMA(ga[k2][0], gb[k2][0], acc[0][0]); acc[0][1] = MFMA(ga[k2][0], gb[k2][1], acc[0][1]);
;             acc[1][0] = MFMA(ga[k2][1], gb[k2][0], acc[1][0]); acc[1][1] = MFMA(ga[k2][1], gb[k2][1], acc[1][1]);
;         }
;         if (kt + 1 < nk) sstore(stset, buf ^ 1, kt + 1);
; #pragma unroll
;         for (int i = 0; i < 8; ++i) { __builtin_amdgcn_sched_group_barrier(0x008, 1, 0); __builtin_amdgcn_sched_group_barrier(0x100, 1, 0); }
; #pragma unroll
;         for (int i = 0; i < 8; ++i) { __builtin_amdgcn_sched_group_barrier(0x008, 1, 0); __builtin_amdgcn_sched_group_barrier(0x200, 1, 0); }
;         __builtin_amdgcn_sched_barrier(0);
;         __syncthreads();
	global_load_dwordx4 v[68:71], v[164:165], off offset:1152
	global_load_dwordx4 v[72:75], v[162:163], off offset:1152
	global_load_dwordx4 v[76:79], v[160:161], off offset:1152
	global_load_dwordx4 v[80:83], v[158:159], off offset:1152
	global_load_dwordx4 v[84:87], v[156:157], off offset:1152
	global_load_dwordx4 v[88:91], v[154:155], off offset:1152
	global_load_dwordx4 v[92:95], v[152:153], off offset:1152
	global_load_dwordx4 v[104:107], v[146:147], off offset:1152
	ds_read_b128 v[202:205], v194
	ds_read_b128 v[206:209], v194 offset:32
	ds_read_b128 v[210:213], v194 offset:4608
	ds_read_b128 v[214:217], v194 offset:4640
	ds_read_b128 v[218:221], v195 offset:36864
	ds_read_b128 v[222:225], v195 offset:36896
	ds_read_b128 v[226:229], v195 offset:41472
	ds_read_b128 v[230:233], v195 offset:41504
	s_waitcnt lgkmcnt(3)
	v_mfma_f32_32x32x16_bf16 v[52:67], v[202:205], v[218:221], v[52:67]
	s_waitcnt lgkmcnt(1)
	v_mfma_f32_32x32x16_bf16 v[36:51], v[202:205], v[226:229], v[36:51]
	v_mfma_f32_32x32x16_bf16 v[4:19], v[210:213], v[226:229], v[4:19]
	s_waitcnt lgkmcnt(0)
	v_mfma_f32_32x32x16_bf16 v[36:51], v[206:209], v[230:233], v[36:51]
	v_mfma_f32_32x32x16_bf16 v[4:19], v[214:217], v[230:233], v[4:19]
	ds_read_b128 v[230:233], v195 offset:41568
	ds_read_b128 v[202:205], v194 offset:4672
	v_mfma_f32_32x32x16_bf16 v[20:35], v[210:213], v[218:221], v[20:35]
	ds_read_b128 v[218:221], v194 offset:4704
	ds_read_b128 v[210:213], v194 offset:64
	v_mfma_f32_32x32x16_bf16 v[52:67], v[206:209], v[222:225], v[52:67]
	ds_read_b128 v[226:229], v195 offset:36960
	ds_read_b128 v[206:209], v195 offset:41536
	v_mfma_f32_32x32x16_bf16 v[20:35], v[214:217], v[222:225], v[20:35]
	ds_read_b128 v[222:225], v195 offset:36928
	ds_read_b128 v[214:217], v194 offset:96
	s_waitcnt lgkmcnt(1)
	v_mfma_f32_32x32x16_bf16 v[52:67], v[210:213], v[222:225], v[52:67]
	s_waitcnt vmcnt(23)
	ds_write_b128 v167, v[96:99] offset:18432
	v_mfma_f32_32x32x16_bf16 v[36:51], v[210:213], v[206:209], v[36:51]
	s_waitcnt vmcnt(22)
	ds_write_b128 v167, v[100:103] offset:55296
	v_mfma_f32_32x32x16_bf16 v[20:35], v[202:205], v[222:225], v[20:35]
	s_waitcnt vmcnt(21)
	ds_write_b128 v190, v[108:111] offset:18432
	v_mfma_f32_32x32x16_bf16 v[4:19], v[202:205], v[206:209], v[4:19]
	s_waitcnt vmcnt(20)
	ds_write_b128 v190, v[112:115] offset:55296
	s_waitcnt lgkmcnt(4)
	v_mfma_f32_32x32x16_bf16 v[52:67], v[214:217], v[226:229], v[52:67]
	s_waitcnt vmcnt(19)
	ds_write_b128 v191, v[116:119] offset:18432
	v_mfma_f32_32x32x16_bf16 v[36:51], v[214:217], v[230:233], v[36:51]
	s_waitcnt vmcnt(18)
	ds_write_b128 v191, v[120:123] offset:55296
	v_mfma_f32_32x32x16_bf16 v[20:35], v[218:221], v[226:229], v[20:35]
	s_waitcnt vmcnt(17)
	ds_write_b128 v192, v[124:127] offset:18432
	v_mfma_f32_32x32x16_bf16 v[4:19], v[218:221], v[230:233], v[4:19]
	s_waitcnt vmcnt(16)
	ds_write_b128 v192, v[128:131] offset:55296
	s_waitcnt lgkmcnt(0)
	s_barrier
	global_load_dwordx4 v[96:99], v[164:165], off offset:1280
	global_load_dwordx4 v[100:103], v[162:163], off offset:1280
	global_load_dwordx4 v[108:111], v[160:161], off offset:1280
	global_load_dwordx4 v[112:115], v[158:159], off offset:1280
	global_load_dwordx4 v[116:119], v[156:157], off offset:1280
	global_load_dwordx4 v[120:123], v[154:155], off offset:1280
	global_load_dwordx4 v[124:127], v[152:153], off offset:1280
	global_load_dwordx4 v[128:131], v[146:147], off offset:1280
	ds_read_b128 v[202:205], v196
	ds_read_b128 v[206:209], v196 offset:32
	ds_read_b128 v[210:213], v196 offset:4608
	ds_read_b128 v[214:217], v196 offset:4640
	ds_read_b128 v[218:221], v197 offset:36864
	ds_read_b128 v[222:225], v197 offset:36896
	ds_read_b128 v[226:229], v197 offset:41472
	ds_read_b128 v[230:233], v197 offset:41504
	s_waitcnt lgkmcnt(3)
	v_mfma_f32_32x32x16_bf16 v[52:67], v[202:205], v[218:221], v[52:67]
	s_waitcnt lgkmcnt(1)
	v_mfma_f32_32x32x16_bf16 v[36:51], v[202:205], v[226:229], v[36:51]
	v_mfma_f32_32x32x16_bf16 v[4:19], v[210:213], v[226:229], v[4:19]
	s_waitcnt lgkmcnt(0)
	v_mfma_f32_32x32x16_bf16 v[36:51], v[206:209], v[230:233], v[36:51]
	v_mfma_f32_32x32x16_bf16 v[4:19], v[214:217], v[230:233], v[4:19]
	ds_read_b128 v[230:233], v197 offset:41568
	ds_read_b128 v[202:205], v196 offset:4672
	v_mfma_f32_32x32x16_bf16 v[20:35], v[210:213], v[218:221], v[20:35]
	ds_read_b128 v[218:221], v196 offset:4704
	ds_read_b128 v[210:213], v196 offset:64
	v_mfma_f32_32x32x16_bf16 v[52:67], v[206:209], v[222:225], v[52:67]
	ds_read_b128 v[226:229], v197 offset:36960
	ds_read_b128 v[206:209], v197 offset:41536
	v_mfma_f32_32x32x16_bf16 v[20:35], v[214:217], v[222:225], v[20:35]
	ds_read_b128 v[222:225], v197 offset:36928
	ds_read_b128 v[214:217], v196 offset:96
	s_waitcnt lgkmcnt(1)
	v_mfma_f32_32x32x16_bf16 v[52:67], v[210:213], v[222:225], v[52:67]
	s_waitcnt vmcnt(23)
	ds_write_b128 v167, v[132:135]
	v_mfma_f32_32x32x16_bf16 v[36:51], v[210:213], v[206:209], v[36:51]
	s_waitcnt vmcnt(22)
	ds_write_b128 v167, v[136:139] offset:36864
	v_mfma_f32_32x32x16_bf16 v[20:35], v[202:205], v[222:225], v[20:35]
	s_waitcnt vmcnt(21)
	ds_write_b128 v190, v[140:143]
	v_mfma_f32_32x32x16_bf16 v[4:19], v[202:205], v[206:209], v[4:19]
	s_waitcnt vmcnt(20)
	ds_write_b128 v190, v[198:201] offset:36864
	s_waitcnt lgkmcnt(4)
	v_mfma_f32_32x32x16_bf16 v[52:67], v[214:217], v[226:229], v[52:67]
	s_waitcnt vmcnt(19)
	ds_write_b128 v191, v[174:177]
	v_mfma_f32_32x32x16_bf16 v[36:51], v[214:217], v[230:233], v[36:51]
	s_waitcnt vmcnt(18)
	ds_write_b128 v191, v[178:181] offset:36864
	v_mfma_f32_32x32x16_bf16 v[20:35], v[218:221], v[226:229], v[20:35]
	s_waitcnt vmcnt(17)
	ds_write_b128 v192, v[242:245]
	v_mfma_f32_32x32x16_bf16 v[4:19], v[218:221], v[230:233], v[4:19]
	s_waitcnt vmcnt(16)
	ds_write_b128 v192, v[246:249] offset:36864
	s_waitcnt lgkmcnt(0)
	s_barrier
; #define MFMA(a, b, c) __builtin_amdgcn_mfma_f32_32x32x16_bf16((a), (b), (c), 0, 0, 0)
; template <class Epi, class ColV>
; DI void gemm_tile(const bf16_t* __restrict__ A, int lda, const bf16_t* __restrict__ Bt, int ldb, int K, int m0, int n0, unsigned char* smem, Epi epi, ColV colv, const bf16_t* __restrict__ HYT = nullptr) {
;     ...
;     auto step = [&](int kt, u32x4 (&ldset)[8], const u32x4 (&stset)[8]) {
;         const int buf = kt & 1;
;         if (kt + 2 < nk) gload(ldset, kt + 2);
;         const bf16_t* Ab = As + (buf * 128 + 64 * wr + li) * LS + 8 * lh;
;         const bf16_t* Bb = Bs + (buf * 128 + 64 * wc + li) * LS + 8 * lh;
;         bf16x8 fa[2][2], fb[2][2], ga[2][2], gb[2][2];
; #pragma unroll
;         for (int k2 = 0; k2 < 2; ++k2) { fa[k2][0] = ld8(Ab + 16 * k2); fa[k2][1] = ld8(Ab + 32 * LS + 16 * k2); fb[k2][0] = ld8(Bb + 16 * k2); fb[k2][1] = ld8(Bb + 32 * LS + 16 * k2); }
;         __builtin_amdgcn_sched_barrier(0);
; #pragma unroll
;         for (int k2 = 0; k2 < 2; ++k2) {
;             acc[0][0] = MFMA(fa[k2][0], fb[k2][0], acc[0][0]); acc[0][1] = MFMA(fa[k2][0], fb[k2][1], acc[0][1]);
;             acc[1][0] = MFMA(fa[k2][1], fb[k2][0], acc[1][0]); acc[1][1] = MFMA(fa[k2][1], fb[k2][1], acc[1][1]);
;         }
; #pragma unroll
;         for (int k2 = 0; k2 < 2; ++k2) { const int ks = 2 + k2; ga[k2][0] = ld8(Ab + 16 * ks); ga[k2][1] = ld8(Ab + 32 * LS + 16 * ks); gb[k2][0] = ld8(Bb + 16 * ks); gb[k2][1] = ld8(Bb + 32 * LS + 16 * ks); }
; #pragma unroll
;         for (int k2 = 0; k2 < 2; ++k2) {
;             acc[0][0] = MFMA(ga[k2][0], gb[k2][0], acc[0][0]); acc[0][1] = MFMA(ga[k2][0], gb[k2][1], acc[0][1]);
;             acc[1][0] = MFMA(ga[k2][1], gb[k2][0], acc[1][0]); acc[1][1] = MFMA(ga[k2][1], gb[k2][1], acc[1][1]);
;         }
;         if (kt + 1 < nk) sstore(stset, buf ^ 1, kt + 1);
; #pragma unroll
;         for (int i = 0; i < 8; ++i) { __builtin_amdgcn_sched_group_barrier(0x008, 1, 0); __builtin_amdgcn_sched_group_barrier(0x100, 1, 0); }
; #pragma unroll
;         for (int i = 0; i < 8; ++i) { __builtin_amdgcn_sched_group_barrier(0x008, 1, 0); __builtin_amdgcn_sched_group_barrier(0x200, 1, 0); }
;         __builtin_amdgcn_sched_barrier(0);
;         __syncthreads();
	global_load_dwordx4 v[132:135], v[164:165], off offset:1408
	global_load_dwordx4 v[136:139], v[162:163], off offset:1408
	global_load_dwordx4 v[140:143], v[160:161], off offset:1408
	global_load_dwordx4 v[198:201], v[158:159], off offset:1408
	global_load_dwordx4 v[174:177], v[156:157], off offset:1408
	global_load_dwordx4 v[178:181], v[154:155], off offset:1408
	global_load_dwordx4 v[242:245], v[152:153], off offset:1408
	global_load_dwordx4 v[246:249], v[146:147], off offset:1408
	ds_read_b128 v[202:205], v194
	ds_read_b128 v[206:209], v194 offset:32
	ds_read_b128 v[210:213], v194 offset:4608
	ds_read_b128 v[214:217], v194 offset:4640
	ds_read_b128 v[218:221], v195 offset:36864
	ds_read_b128 v[222:225], v195 offset:36896
	ds_read_b128 v[226:229], v195 offset:41472
	ds_read_b128 v[230:233], v195 offset:41504
	s_waitcnt lgkmcnt(3)
	v_mfma_f32_32x32x16_bf16 v[52:67], v[202:205], v[218:221], v[52:67]
	s_waitcnt lgkmcnt(1)
	v_mfma_f32_32x32x16_bf16 v[36:51], v[202:205], v[226:229], v[36:51]
	v_mfma_f32_32x32x16_bf16 v[4:19], v[210:213], v[226:229], v[4:19]
	s_waitcnt lgkmcnt(0)
	v_mfma_f32_32x32x16_bf16 v[36:51], v[206:209], v[230:233], v[36:51]
	v_mfma_f32_32x32x16_bf16 v[4:19], v[214:217], v[230:233], v[4:19]
	ds_read_b128 v[230:233], v195 offset:41568
	ds_read_b128 v[202:205], v194 offset:4672
	v_mfma_f32_32x32x16_bf16 v[20:35], v[210:213], v[218:221], v[20:35]
	ds_read_b128 v[218:221], v194 offset:4704
	ds_read_b128 v[210:213], v194 offset:64
	v_mfma_f32_32x32x16_bf16 v[52:67], v[206:209], v[222:225], v[52:67]
	ds_read_b128 v[226:229], v195 offset:36960
	ds_read_b128 v[206:209], v195 offset:41536
	v_mfma_f32_32x32x16_bf16 v[20:35], v[214:217], v[222:225], v[20:35]
	ds_read_b128 v[222:225], v195 offset:36928
	ds_read_b128 v[214:217], v194 offset:96
	s_waitcnt lgkmcnt(1)
	v_mfma_f32_32x32x16_bf16 v[52:67], v[210:213], v[222:225], v[52:67]
	s_waitcnt vmcnt(23)
	ds_write_b128 v167, v[68:71] offset:18432
	v_mfma_f32_32x32x16_bf16 v[36:51], v[210:213], v[206:209], v[36:51]
	s_waitcnt vmcnt(22)
	ds_write_b128 v167, v[72:75] offset:55296
	v_mfma_f32_32x32x16_bf16 v[20:35], v[202:205], v[222:225], v[20:35]
	s_waitcnt vmcnt(21)
	ds_write_b128 v190, v[76:79] offset:18432
	v_mfma_f32_32x32x16_bf16 v[4:19], v[202:205], v[206:209], v[4:19]
	s_waitcnt vmcnt(20)
	ds_write_b128 v190, v[80:83] offset:55296
	s_waitcnt lgkmcnt(4)
	v_mfma_f32_32x32x16_bf16 v[52:67], v[214:217], v[226:229], v[52:67]
	s_waitcnt vmcnt(19)
	ds_write_b128 v191, v[84:87] offset:18432
	v_mfma_f32_32x32x16_bf16 v[36:51], v[214:217], v[230:233], v[36:51]
	s_waitcnt vmcnt(18)
	ds_write_b128 v191, v[88:91] offset:55296
	v_mfma_f32_32x32x16_bf16 v[20:35], v[218:221], v[226:229], v[20:35]
	s_waitcnt vmcnt(17)
	ds_write_b128 v192, v[92:95] offset:18432
	v_mfma_f32_32x32x16_bf16 v[4:19], v[218:221], v[230:233], v[4:19]
	s_waitcnt vmcnt(16)
	ds_write_b128 v192, v[104:107] offset:55296
	s_waitcnt lgkmcnt(0)
	s_barrier
	global_load_dwordx4 v[68:71], v[164:165], off offset:1536
	global_load_dwordx4 v[72:75], v[162:163], off offset:1536
	global_load_dwordx4 v[76:79], v[160:161], off offset:1536
	global_load_dwordx4 v[80:83], v[158:159], off offset:1536
	global_load_dwordx4 v[84:87], v[156:157], off offset:1536
	global_load_dwordx4 v[88:91], v[154:155], off offset:1536
	global_load_dwordx4 v[92:95], v[152:153], off offset:1536
	global_load_dwordx4 v[104:107], v[146:147], off offset:1536
	ds_read_b128 v[202:205], v196
	ds_read_b128 v[206:209], v196 offset:32
	ds_read_b128 v[210:213], v196 offset:4608
	ds_read_b128 v[214:217], v196 offset:4640
	ds_read_b128 v[218:221], v197 offset:36864
	ds_read_b128 v[222:225], v197 offset:36896
	ds_read_b128 v[226:229], v197 offset:41472
	ds_read_b128 v[230:233], v197 offset:41504
	s_waitcnt lgkmcnt(3)
	v_mfma_f32_32x32x16_bf16 v[52:67], v[202:205], v[218:221], v[52:67]
	s_waitcnt lgkmcnt(1)
	v_mfma_f32_32x32x16_bf16 v[36:51], v[202:205], v[226:229], v[36:51]
	v_mfma_f32_32x32x16_bf16 v[4:19], v[210:213], v[226:229], v[4:19]
	s_waitcnt lgkmcnt(0)
	v_mfma_f32_32x32x16_bf16 v[36:51], v[206:209], v[230:233], v[36:51]
	v_mfma_f32_32x32x16_bf16 v[4:19], v[214:217], v[230:233], v[4:19]
	ds_read_b128 v[230:233], v197 offset:41568
	ds_read_b128 v[202:205], v196 offset:4672
	v_mfma_f32_32x32x16_bf16 v[20:35], v[210:213], v[218:221], v[20:35]
	ds_read_b128 v[218:221], v196 offset:4704
	ds_read_b128 v[210:213], v196 offset:64
	v_mfma_f32_32x32x16_bf16 v[52:67], v[206:209], v[222:225], v[52:67]
	ds_read_b128 v[226:229], v197 offset:36960
	ds_read_b128 v[206:209], v197 offset:41536
	v_mfma_f32_32x32x16_bf16 v[20:35], v[214:217], v[222:225], v[20:35]
	ds_read_b128 v[222:225], v197 offset:36928
	ds_read_b128 v[214:217], v196 offset:96
	s_waitcnt lgkmcnt(1)
	v_mfma_f32_32x32x16_bf16 v[52:67], v[210:213], v[222:225], v[52:67]
	s_waitcnt vmcnt(23)
	ds_write_b128 v167, v[96:99]
	v_mfma_f32_32x32x16_bf16 v[36:51], v[210:213], v[206:209], v[36:51]
	s_waitcnt vmcnt(22)
	ds_write_b128 v167, v[100:103] offset:36864
	v_mfma_f32_32x32x16_bf16 v[20:35], v[202:205], v[222:225], v[20:35]
	s_waitcnt vmcnt(21)
	ds_write_b128 v190, v[108:111]
	v_mfma_f32_32x32x16_bf16 v[4:19], v[202:205], v[206:209], v[4:19]
	s_waitcnt vmcnt(20)
	ds_write_b128 v190, v[112:115] offset:36864
	s_waitcnt lgkmcnt(4)
	v_mfma_f32_32x32x16_bf16 v[52:67], v[214:217], v[226:229], v[52:67]
	s_waitcnt vmcnt(19)
	ds_write_b128 v191, v[116:119]
	v_mfma_f32_32x32x16_bf16 v[36:51], v[214:217], v[230:233], v[36:51]
	s_waitcnt vmcnt(18)
	ds_write_b128 v191, v[120:123] offset:36864
	v_mfma_f32_32x32x16_bf16 v[20:35], v[218:221], v[226:229], v[20:35]
	s_waitcnt vmcnt(17)
	ds_write_b128 v192, v[124:127]
	v_mfma_f32_32x32x16_bf16 v[4:19], v[218:221], v[230:233], v[4:19]
	s_waitcnt vmcnt(16)
	ds_write_b128 v192, v[128:131] offset:36864
	s_waitcnt lgkmcnt(0)
	s_barrier
; #define MFMA(a, b, c) __builtin_amdgcn_mfma_f32_32x32x16_bf16((a), (b), (c), 0, 0, 0)
; template <class Epi, class ColV>
; DI void gemm_tile(const bf16_t* __restrict__ A, int lda, const bf16_t* __restrict__ Bt, int ldb, int K, int m0, int n0, unsigned char* smem, Epi epi, ColV colv, const bf16_t* __restrict__ HYT = nullptr) {
;     ...
;     auto step = [&](int kt, u32x4 (&ldset)[8], const u32x4 (&stset)[8]) {
;         const int buf = kt & 1;
;         if (kt + 2 < nk) gload(ldset, kt + 2);
;         const bf16_t* Ab = As + (buf * 128 + 64 * wr + li) * LS + 8 * lh;
;         const bf16_t* Bb = Bs + (buf * 128 + 64 * wc + li) * LS + 8 * lh;
;         bf16x8 fa[2][2], fb[2][2], ga[2][2], gb[2][2];
; #pragma unroll
;         for (int k2 = 0; k2 < 2; ++k2) { fa[k2][0] = ld8(Ab + 16 * k2); fa[k2][1] = ld8(Ab + 32 * LS + 16 * k2); fb[k2][0] = ld8(Bb + 16 * k2); fb[k2][1] = ld8(Bb + 32 * LS + 16 * k2); }
;         __builtin_amdgcn_sched_barrier(0);
; #pragma unroll
;         for (int k2 = 0; k2 < 2; ++k2) {
;             acc[0][0] = MFMA(fa[k2][0], fb[k2][0], acc[0][0]); acc[0][1] = MFMA(fa[k2][0], fb[k2][1], acc[0][1]);
;             acc[1][0] = MFMA(fa[k2][1], fb[k2][0], acc[1][0]); acc[1][1] = MFMA(fa[k2][1], fb[k2][1], acc[1][1]);
;         }
; #pragma unroll
;         for (int k2 = 0; k2 < 2; ++k2) { const int ks = 2 + k2; ga[k2][0] = ld8(Ab + 16 * ks); ga[k2][1] = ld8(Ab + 32 * LS + 16 * ks); gb[k2][0] = ld8(Bb + 16 * ks); gb[k2][1] = ld8(Bb + 32 * LS + 16 * ks); }
; #pragma unroll
;         for (int k2 = 0; k2 < 2; ++k2) {
;             acc[0][0] = MFMA(ga[k2][0], gb[k2][0], acc[0][0]); acc[0][1] = MFMA(ga[k2][0], gb[k2][1], acc[0][1]);
;             acc[1][0] = MFMA(ga[k2][1], gb[k2][0], acc[1][0]); acc[1][1] = MFMA(ga[k2][1], gb[k2][1], acc[1][1]);
;         }
;         if (kt + 1 < nk) sstore(stset, buf ^ 1, kt + 1);
; #pragma unroll
;         for (int i = 0; i < 8; ++i) { __builtin_amdgcn_sched_group_barrier(0x008, 1, 0); __builtin_amdgcn_sched_group_barrier(0x100, 1, 0); }
; #pragma unroll
;         for (int i = 0; i < 8; ++i) { __builtin_amdgcn_sched_group_barrier(0x008, 1, 0); __builtin_amdgcn_sched_group_barrier(0x200, 1, 0); }
;         __builtin_amdgcn_sched_barrier(0);
;         __syncthreads();
	global_load_dwordx4 v[96:99], v[164:165], off offset:1664
	global_load_dwordx4 v[100:103], v[162:163], off offset:1664
	global_load_dwordx4 v[108:111], v[160:161], off offset:1664
	global_load_dwordx4 v[112:115], v[158:159], off offset:1664
	global_load_dwordx4 v[116:119], v[156:157], off offset:1664
	global_load_dwordx4 v[120:123], v[154:155], off offset:1664
	global_load_dwordx4 v[124:127], v[152:153], off offset:1664
	global_load_dwordx4 v[128:131], v[146:147], off offset:1664
	ds_read_b128 v[202:205], v194
	ds_read_b128 v[206:209], v194 offset:32
	ds_read_b128 v[210:213], v194 offset:4608
	ds_read_b128 v[214:217], v194 offset:4640
	ds_read_b128 v[218:221], v195 offset:36864
	ds_read_b128 v[222:225], v195 offset:36896
	ds_read_b128 v[226:229], v195 offset:41472
	ds_read_b128 v[230:233], v195 offset:41504
	s_waitcnt lgkmcnt(3)
	v_mfma_f32_32x32x16_bf16 v[52:67], v[202:205], v[218:221], v[52:67]
	s_waitcnt lgkmcnt(1)
	v_mfma_f32_32x32x16_bf16 v[36:51], v[202:205], v[226:229], v[36:51]
	v_mfma_f32_32x32x16_bf16 v[4:19], v[210:213], v[226:229], v[4:19]
	s_waitcnt lgkmcnt(0)
	v_mfma_f32_32x32x16_bf16 v[36:51], v[206:209], v[230:233], v[36:51]
	v_mfma_f32_32x32x16_bf16 v[4:19], v[214:217], v[230:233], v[4:19]
	ds_read_b128 v[230:233], v195 offset:41568
	ds_read_b128 v[202:205], v194 offset:4672
	v_mfma_f32_32x32x16_bf16 v[20:35], v[210:213], v[218:221], v[20:35]
	ds_read_b128 v[218:221], v194 offset:4704
	ds_read_b128 v[210:213], v194 offset:64
	v_mfma_f32_32x32x16_bf16 v[52:67], v[206:209], v[222:225], v[52:67]
	ds_read_b128 v[226:229], v195 offset:36960
	ds_read_b128 v[206:209], v195 offset:41536
	v_mfma_f32_32x32x16_bf16 v[20:35], v[214:217], v[222:225], v[20:35]
	ds_read_b128 v[222:225], v195 offset:36928
	ds_read_b128 v[214:217], v194 offset:96
	s_waitcnt lgkmcnt(1)
	v_mfma_f32_32x32x16_bf16 v[52:67], v[210:213], v[222:225], v[52:67]
	s_waitcnt vmcnt(23)
	ds_write_b128 v167, v[132:135] offset:18432
	v_mfma_f32_32x32x16_bf16 v[36:51], v[210:213], v[206:209], v[36:51]
	s_waitcnt vmcnt(22)
	ds_write_b128 v167, v[136:139] offset:55296
	v_mfma_f32_32x32x16_bf16 v[20:35], v[202:205], v[222:225], v[20:35]
	s_waitcnt vmcnt(21)
	ds_write_b128 v190, v[140:143] offset:18432
	v_mfma_f32_32x32x16_bf16 v[4:19], v[202:205], v[206:209], v[4:19]
	s_waitcnt vmcnt(20)
	ds_write_b128 v190, v[198:201] offset:55296
	s_waitcnt lgkmcnt(4)
	v_mfma_f32_32x32x16_bf16 v[52:67], v[214:217], v[226:229], v[52:67]
	s_waitcnt vmcnt(19)
	ds_write_b128 v191, v[174:177] offset:18432
	v_mfma_f32_32x32x16_bf16 v[36:51], v[214:217], v[230:233], v[36:51]
	s_waitcnt vmcnt(18)
	ds_write_b128 v191, v[178:181] offset:55296
	v_mfma_f32_32x32x16_bf16 v[20:35], v[218:221], v[226:229], v[20:35]
	s_waitcnt vmcnt(17)
	ds_write_b128 v192, v[242:245] offset:18432
	v_mfma_f32_32x32x16_bf16 v[4:19], v[218:221], v[230:233], v[4:19]
	s_waitcnt vmcnt(16)
	ds_write_b128 v192, v[246:249] offset:55296
	s_waitcnt lgkmcnt(0)
	s_barrier
	global_load_dwordx4 v[132:135], v[164:165], off offset:1792
	global_load_dwordx4 v[136:139], v[162:163], off offset:1792
	global_load_dwordx4 v[140:143], v[160:161], off offset:1792
	global_load_dwordx4 v[198:201], v[158:159], off offset:1792
	global_load_dwordx4 v[174:177], v[156:157], off offset:1792
	global_load_dwordx4 v[178:181], v[154:155], off offset:1792
	global_load_dwordx4 v[242:245], v[152:153], off offset:1792
	global_load_dwordx4 v[246:249], v[146:147], off offset:1792
	ds_read_b128 v[202:205], v196
	ds_read_b128 v[206:209], v196 offset:32
	ds_read_b128 v[210:213], v196 offset:4608
	ds_read_b128 v[214:217], v196 offset:4640
	ds_read_b128 v[218:221], v197 offset:36864
	ds_read_b128 v[222:225], v197 offset:36896
	ds_read_b128 v[226:229], v197 offset:41472
	ds_read_b128 v[230:233], v197 offset:41504
	s_waitcnt lgkmcnt(3)
	v_mfma_f32_32x32x16_bf16 v[52:67], v[202:205], v[218:221], v[52:67]
	s_waitcnt lgkmcnt(1)
	v_mfma_f32_32x32x16_bf16 v[36:51], v[202:205], v[226:229], v[36:51]
	v_mfma_f32_32x32x16_bf16 v[4:19], v[210:213], v[226:229], v[4:19]
	s_waitcnt lgkmcnt(0)
	v_mfma_f32_32x32x16_bf16 v[36:51], v[206:209], v[230:233], v[36:51]
	v_mfma_f32_32x32x16_bf16 v[4:19], v[214:217], v[230:233], v[4:19]
	ds_read_b128 v[230:233], v197 offset:41568
	ds_read_b128 v[202:205], v196 offset:4672
	v_mfma_f32_32x32x16_bf16 v[20:35], v[210:213], v[218:221], v[20:35]
	ds_read_b128 v[218:221], v196 offset:4704
	ds_read_b128 v[210:213], v196 offset:64
	v_mfma_f32_32x32x16_bf16 v[52:67], v[206:209], v[222:225], v[52:67]
	ds_read_b128 v[226:229], v197 offset:36960
	ds_read_b128 v[206:209], v197 offset:41536
	v_mfma_f32_32x32x16_bf16 v[20:35], v[214:217], v[222:225], v[20:35]
	ds_read_b128 v[222:225], v197 offset:36928
	ds_read_b128 v[214:217], v196 offset:96
	s_waitcnt lgkmcnt(1)
	v_mfma_f32_32x32x16_bf16 v[52:67], v[210:213], v[222:225], v[52:67]
	s_waitcnt vmcnt(23)
	ds_write_b128 v167, v[68:71]
	v_mfma_f32_32x32x16_bf16 v[36:51], v[210:213], v[206:209], v[36:51]
	s_waitcnt vmcnt(22)
	ds_write_b128 v167, v[72:75] offset:36864
	v_mfma_f32_32x32x16_bf16 v[20:35], v[202:205], v[222:225], v[20:35]
	s_waitcnt vmcnt(21)
	ds_write_b128 v190, v[76:79]
	v_mfma_f32_32x32x16_bf16 v[4:19], v[202:205], v[206:209], v[4:19]
	s_waitcnt vmcnt(20)
	ds_write_b128 v190, v[80:83] offset:36864
	s_waitcnt lgkmcnt(4)
	v_mfma_f32_32x32x16_bf16 v[52:67], v[214:217], v[226:229], v[52:67]
	s_waitcnt vmcnt(19)
	ds_write_b128 v191, v[84:87]
	v_mfma_f32_32x32x16_bf16 v[36:51], v[214:217], v[230:233], v[36:51]
	s_waitcnt vmcnt(18)
	ds_write_b128 v191, v[88:91] offset:36864
	v_mfma_f32_32x32x16_bf16 v[20:35], v[218:221], v[226:229], v[20:35]
	s_waitcnt vmcnt(17)
	ds_write_b128 v192, v[92:95]
	v_mfma_f32_32x32x16_bf16 v[4:19], v[218:221], v[230:233], v[4:19]
	s_waitcnt vmcnt(16)
	ds_write_b128 v192, v[104:107] offset:36864
	s_waitcnt lgkmcnt(0)
	s_barrier
; #define MFMA(a, b, c) __builtin_amdgcn_mfma_f32_32x32x16_bf16((a), (b), (c), 0, 0, 0)
; template <class Epi, class ColV>
; DI void gemm_tile(const bf16_t* __restrict__ A, int lda, const bf16_t* __restrict__ Bt, int ldb, int K, int m0, int n0, unsigned char* smem, Epi epi, ColV colv, const bf16_t* __restrict__ HYT = nullptr) {
;     ...
;     auto step = [&](int kt, u32x4 (&ldset)[8], const u32x4 (&stset)[8]) {
;         const int buf = kt & 1;
;         if (kt + 2 < nk) gload(ldset, kt + 2);
;         const bf16_t* Ab = As + (buf * 128 + 64 * wr + li) * LS + 8 * lh;
;         const bf16_t* Bb = Bs + (buf * 128 + 64 * wc + li) * LS + 8 * lh;
;         bf16x8 fa[2][2], fb[2][2], ga[2][2], gb[2][2];
; #pragma unroll
;         for (int k2 = 0; k2 < 2; ++k2) { fa[k2][0] = ld8(Ab + 16 * k2); fa[k2][1] = ld8(Ab + 32 * LS + 16 * k2); fb[k2][0] = ld8(Bb + 16 * k2); fb[k2][1] = ld8(Bb + 32 * LS + 16 * k2); }
;         __builtin_amdgcn_sched_barrier(0);
; #pragma unroll
;         for (int k2 = 0; k2 < 2; ++k2) {
;             acc[0][0] = MFMA(fa[k2][0], fb[k2][0], acc[0][0]); acc[0][1] = MFMA(fa[k2][0], fb[k2][1], acc[0][1]);
;             acc[1][0] = MFMA(fa[k2][1], fb[k2][0], acc[1][0]); acc[1][1] = MFMA(fa[k2][1], fb[k2][1], acc[1][1]);
;         }
; #pragma unroll
;         for (int k2 = 0; k2 < 2; ++k2) { const int ks = 2 + k2; ga[k2][0] = ld8(Ab + 16 * ks); ga[k2][1] = ld8(Ab + 32 * LS + 16 * ks); gb[k2][0] = ld8(Bb + 16 * ks); gb[k2][1] = ld8(Bb + 32 * LS + 16 * ks); }
; #pragma unroll
;         for (int k2 = 0; k2 < 2; ++k2) {
;             acc[0][0] = MFMA(ga[k2][0], gb[k2][0], acc[0][0]); acc[0][1] = MFMA(ga[k2][0], gb[k2][1], acc[0][1]);
;             acc[1][0] = MFMA(ga[k2][1], gb[k2][0], acc[1][0]); acc[1][1] = MFMA(ga[k2][1], gb[k2][1], acc[1][1]);
;         }
;         if (kt + 1 < nk) sstore(stset, buf ^ 1, kt + 1);
; #pragma unroll
;         for (int i = 0; i < 8; ++i) { __builtin_amdgcn_sched_group_barrier(0x008, 1, 0); __builtin_amdgcn_sched_group_barrier(0x100, 1, 0); }
; #pragma unroll
;         for (int i = 0; i < 8; ++i) { __builtin_amdgcn_sched_group_barrier(0x008, 1, 0); __builtin_amdgcn_sched_group_barrier(0x200, 1, 0); }
;         __builtin_amdgcn_sched_barrier(0);
;         __syncthreads();
	global_load_dwordx4 v[68:71], v[164:165], off offset:1920
	global_load_dwordx4 v[72:75], v[162:163], off offset:1920
	global_load_dwordx4 v[76:79], v[160:161], off offset:1920
	global_load_dwordx4 v[80:83], v[158:159], off offset:1920
	global_load_dwordx4 v[84:87], v[156:157], off offset:1920
	global_load_dwordx4 v[88:91], v[154:155], off offset:1920
	global_load_dwordx4 v[92:95], v[152:153], off offset:1920
	global_load_dwordx4 v[104:107], v[146:147], off offset:1920
	ds_read_b128 v[202:205], v194
	ds_read_b128 v[206:209], v194 offset:32
	ds_read_b128 v[210:213], v194 offset:4608
	ds_read_b128 v[214:217], v194 offset:4640
	ds_read_b128 v[218:221], v195 offset:36864
	ds_read_b128 v[222:225], v195 offset:36896
	ds_read_b128 v[226:229], v195 offset:41472
	ds_read_b128 v[230:233], v195 offset:41504
	s_waitcnt lgkmcnt(3)
	v_mfma_f32_32x32x16_bf16 v[52:67], v[202:205], v[218:221], v[52:67]
	s_waitcnt lgkmcnt(1)
	v_mfma_f32_32x32x16_bf16 v[36:51], v[202:205], v[226:229], v[36:51]
	v_mfma_f32_32x32x16_bf16 v[4:19], v[210:213], v[226:229], v[4:19]
	s_waitcnt lgkmcnt(0)
	v_mfma_f32_32x32x16_bf16 v[36:51], v[206:209], v[230:233], v[36:51]
	v_mfma_f32_32x32x16_bf16 v[4:19], v[214:217], v[230:233], v[4:19]
	ds_read_b128 v[230:233], v195 offset:41568
	ds_read_b128 v[202:205], v194 offset:4672
	v_mfma_f32_32x32x16_bf16 v[20:35], v[210:213], v[218:221], v[20:35]
	ds_read_b128 v[218:221], v194 offset:4704
	ds_read_b128 v[210:213], v194 offset:64
	v_mfma_f32_32x32x16_bf16 v[52:67], v[206:209], v[222:225], v[52:67]
	ds_read_b128 v[226:229], v195 offset:36960
	ds_read_b128 v[206:209], v195 offset:41536
	v_mfma_f32_32x32x16_bf16 v[20:35], v[214:217], v[222:225], v[20:35]
	ds_read_b128 v[222:225], v195 offset:36928
	ds_read_b128 v[214:217], v194 offset:96
	s_waitcnt lgkmcnt(1)
	v_mfma_f32_32x32x16_bf16 v[52:67], v[210:213], v[222:225], v[52:67]
	s_waitcnt vmcnt(23)
	ds_write_b128 v167, v[96:99] offset:18432
	v_mfma_f32_32x32x16_bf16 v[36:51], v[210:213], v[206:209], v[36:51]
	s_waitcnt vmcnt(22)
	ds_write_b128 v167, v[100:103] offset:55296
	v_mfma_f32_32x32x16_bf16 v[20:35], v[202:205], v[222:225], v[20:35]
	s_waitcnt vmcnt(21)
	ds_write_b128 v190, v[108:111] offset:18432
	v_mfma_f32_32x32x16_bf16 v[4:19], v[202:205], v[206:209], v[4:19]
	s_waitcnt vmcnt(20)
	ds_write_b128 v190, v[112:115] offset:55296
	s_waitcnt lgkmcnt(4)
	v_mfma_f32_32x32x16_bf16 v[52:67], v[214:217], v[226:229], v[52:67]
	s_waitcnt vmcnt(19)
	ds_write_b128 v191, v[116:119] offset:18432
	v_mfma_f32_32x32x16_bf16 v[36:51], v[214:217], v[230:233], v[36:51]
	s_waitcnt vmcnt(18)
	ds_write_b128 v191, v[120:123] offset:55296
	v_mfma_f32_32x32x16_bf16 v[20:35], v[218:221], v[226:229], v[20:35]
	s_waitcnt vmcnt(17)
	ds_write_b128 v192, v[124:127] offset:18432
	v_mfma_f32_32x32x16_bf16 v[4:19], v[218:221], v[230:233], v[4:19]
	s_waitcnt vmcnt(16)
	ds_write_b128 v192, v[128:131] offset:55296
	s_waitcnt lgkmcnt(0)
	s_barrier
	ds_read_b128 v[202:205], v196
	ds_read_b128 v[206:209], v196 offset:32
	ds_read_b128 v[210:213], v196 offset:4608
	ds_read_b128 v[214:217], v196 offset:4640
	ds_read_b128 v[218:221], v197 offset:36864
	ds_read_b128 v[222:225], v197 offset:36896
	ds_read_b128 v[226:229], v197 offset:41472
	ds_read_b128 v[230:233], v197 offset:41504
	s_waitcnt lgkmcnt(3)
	v_mfma_f32_32x32x16_bf16 v[52:67], v[202:205], v[218:221], v[52:67]
	s_waitcnt lgkmcnt(1)
	v_mfma_f32_32x32x16_bf16 v[36:51], v[202:205], v[226:229], v[36:51]
	v_mfma_f32_32x32x16_bf16 v[4:19], v[210:213], v[226:229], v[4:19]
	s_waitcnt lgkmcnt(0)
	v_mfma_f32_32x32x16_bf16 v[36:51], v[206:209], v[230:233], v[36:51]
	v_mfma_f32_32x32x16_bf16 v[4:19], v[214:217], v[230:233], v[4:19]
	ds_read_b128 v[230:233], v197 offset:41568
	ds_read_b128 v[202:205], v196 offset:4672
	v_mfma_f32_32x32x16_bf16 v[20:35], v[210:213], v[218:221], v[20:35]
	ds_read_b128 v[218:221], v196 offset:4704
	ds_read_b128 v[210:213], v196 offset:64
	v_mfma_f32_32x32x16_bf16 v[52:67], v[206:209], v[222:225], v[52:67]
	ds_read_b128 v[226:229], v197 offset:36960
	ds_read_b128 v[206:209], v197 offset:41536
	v_mfma_f32_32x32x16_bf16 v[20:35], v[214:217], v[222:225], v[20:35]
	ds_read_b128 v[222:225], v197 offset:36928
	ds_read_b128 v[214:217], v196 offset:96
	s_waitcnt lgkmcnt(1)
	v_mfma_f32_32x32x16_bf16 v[52:67], v[210:213], v[222:225], v[52:67]
	s_waitcnt vmcnt(15)
	ds_write_b128 v167, v[132:135]
	v_mfma_f32_32x32x16_bf16 v[36:51], v[210:213], v[206:209], v[36:51]
	s_waitcnt vmcnt(14)
	ds_write_b128 v167, v[136:139] offset:36864
	v_mfma_f32_32x32x16_bf16 v[20:35], v[202:205], v[222:225], v[20:35]
	s_waitcnt vmcnt(13)
	ds_write_b128 v190, v[140:143]
	v_mfma_f32_32x32x16_bf16 v[4:19], v[202:205], v[206:209], v[4:19]
	s_waitcnt vmcnt(12)
	ds_write_b128 v190, v[198:201] offset:36864
	s_waitcnt lgkmcnt(4)
	v_mfma_f32_32x32x16_bf16 v[52:67], v[214:217], v[226:229], v[52:67]
	s_waitcnt vmcnt(11)
	ds_write_b128 v191, v[174:177]
	v_mfma_f32_32x32x16_bf16 v[36:51], v[214:217], v[230:233], v[36:51]
	s_waitcnt vmcnt(10)
	ds_write_b128 v191, v[178:181] offset:36864
	v_mfma_f32_32x32x16_bf16 v[20:35], v[218:221], v[226:229], v[20:35]
	s_waitcnt vmcnt(9)
	ds_write_b128 v192, v[242:245]
	v_mfma_f32_32x32x16_bf16 v[4:19], v[218:221], v[230:233], v[4:19]
	s_waitcnt vmcnt(8)
	ds_write_b128 v192, v[246:249] offset:36864
	s_waitcnt lgkmcnt(0)
	s_barrier
; template <class Epi, class ColV>
; DI void gemm_tile(const bf16_t* __restrict__ A, int lda, const bf16_t* __restrict__ Bt, int ldb, int K, int m0, int n0, unsigned char* smem, Epi epi, ColV colv, const bf16_t* __restrict__ HYT = nullptr) {
;     ...
;     auto step = [&](int kt, u32x4 (&ldset)[8], const u32x4 (&stset)[8]) {
;         const int buf = kt & 1;
;         if (kt + 2 < nk) gload(ldset, kt + 2);
;         const bf16_t* Ab = As + (buf * 128 + 64 * wr + li) * LS + 8 * lh;
;         const bf16_t* Bb = Bs + (buf * 128 + 64 * wc + li) * LS + 8 * lh;
;         bf16x8 fa[2][2], fb[2][2], ga[2][2], gb[2][2];
; #pragma unroll
;         for (int k2 = 0; k2 < 2; ++k2) { fa[k2][0] = ld8(Ab + 16 * k2); fa[k2][1] = ld8(Ab + 32 * LS + 16 * k2); fb[k2][0] = ld8(Bb + 16 * k2); fb[k2][1] = ld8(Bb + 32 * LS + 16 * k2); }
;         __builtin_amdgcn_sched_barrier(0);
; #pragma unroll
;         for (int k2 = 0; k2 < 2; ++k2) {
;             acc[0][0] = MFMA(fa[k2][0], fb[k2][0], acc[0][0]); acc[0][1] = MFMA(fa[k2][0], fb[k2][1], acc[0][1]);
;             acc[1][0] = MFMA(fa[k2][1], fb[k2][0], acc[1][0]); acc[1][1] = MFMA(fa[k2][1], fb[k2][1], acc[1][1]);
;         }
; #pragma unroll
;         for (int k2 = 0; k2 < 2; ++k2) { const int ks = 2 + k2; ga[k2][0] = ld8(Ab + 16 * ks); ga[k2][1] = ld8(Ab + 32 * LS + 16 * ks); gb[k2][0] = ld8(Bb + 16 * ks); gb[k2][1] = ld8(Bb + 32 * LS + 16 * ks); }
; #pragma unroll
;         for (int k2 = 0; k2 < 2; ++k2) {
;             acc[0][0] = MFMA(ga[k2][0], gb[k2][0], acc[0][0]); acc[0][1] = MFMA(ga[k2][0], gb[k2][1], acc[0][1]);
;             acc[1][0] = MFMA(ga[k2][1], gb[k2][0], acc[1][0]); acc[1][1] = MFMA(ga[k2][1], gb[k2][1], acc[1][1]);
;         }
;         if (kt + 1 < nk) sstore(stset, buf ^ 1, kt + 1);
; #pragma unroll
;         for (int i = 0; i < 8; ++i) { __builtin_amdgcn_sched_group_barrier(0x008, 1, 0); __builtin_amdgcn_sched_group_barrier(0x100, 1, 0); }
; #pragma unroll
;         for (int i = 0; i < 8; ++i) { __builtin_amdgcn_sched_group_barrier(0x008, 1, 0); __builtin_amdgcn_sched_group_barrier(0x200, 1, 0); }
;         __builtin_amdgcn_sched_barrier(0);
;         __syncthreads();
;     };
;     gload(R0, 0); gload(R1, 1);
;     sstore(R0, 0, 0); __syncthreads();
;     for (int kt = 0; kt < nk; kt += 2) {
;         step(kt, R0, R1);
;         if (kt + 1 < nk) step(kt + 1, R1, R0);
;     }
	ds_read_b128 v[202:205], v194
	ds_read_b128 v[206:209], v194 offset:32
	ds_read_b128 v[210:213], v194 offset:4608
	ds_read_b128 v[214:217], v194 offset:4640
	ds_read_b128 v[218:221], v195 offset:36864
	ds_read_b128 v[222:225], v195 offset:36896
	ds_read_b128 v[226:229], v195 offset:41472
	ds_read_b128 v[230:233], v195 offset:41504
	s_waitcnt lgkmcnt(3)
	v_mfma_f32_32x32x16_bf16 v[52:67], v[202:205], v[218:221], v[52:67]
	s_waitcnt lgkmcnt(1)
	v_mfma_f32_32x32x16_bf16 v[36:51], v[202:205], v[226:229], v[36:51]
	v_mfma_f32_32x32x16_bf16 v[4:19], v[210:213], v[226:229], v[4:19]
	s_waitcnt lgkmcnt(0)
	v_mfma_f32_32x32x16_bf16 v[36:51], v[206:209], v[230:233], v[36:51]
	v_mfma_f32_32x32x16_bf16 v[4:19], v[214:217], v[230:233], v[4:19]
	ds_read_b128 v[230:233], v195 offset:41568
	ds_read_b128 v[202:205], v194 offset:4672
	v_mfma_f32_32x32x16_bf16 v[20:35], v[210:213], v[218:221], v[20:35]
	ds_read_b128 v[218:221], v194 offset:4704
	ds_read_b128 v[210:213], v194 offset:64
	v_mfma_f32_32x32x16_bf16 v[52:67], v[206:209], v[222:225], v[52:67]
	ds_read_b128 v[226:229], v195 offset:36960
	ds_read_b128 v[206:209], v195 offset:41536
	v_mfma_f32_32x32x16_bf16 v[20:35], v[214:217], v[222:225], v[20:35]
	ds_read_b128 v[222:225], v195 offset:36928
	ds_read_b128 v[214:217], v194 offset:96
	s_waitcnt lgkmcnt(1)
	v_mfma_f32_32x32x16_bf16 v[52:67], v[210:213], v[222:225], v[52:67]
	s_waitcnt vmcnt(7)
	ds_write_b128 v167, v[68:71] offset:18432
	v_mfma_f32_32x32x16_bf16 v[36:51], v[210:213], v[206:209], v[36:51]
	s_waitcnt vmcnt(6)
	ds_write_b128 v167, v[72:75] offset:55296
	v_mfma_f32_32x32x16_bf16 v[20:35], v[202:205], v[222:225], v[20:35]
	s_waitcnt vmcnt(5)
	ds_write_b128 v190, v[76:79] offset:18432
	v_mfma_f32_32x32x16_bf16 v[4:19], v[202:205], v[206:209], v[4:19]
	s_waitcnt vmcnt(4)
	ds_write_b128 v190, v[80:83] offset:55296
	s_waitcnt lgkmcnt(4)
	v_mfma_f32_32x32x16_bf16 v[52:67], v[214:217], v[226:229], v[52:67]
	s_waitcnt vmcnt(3)
	ds_write_b128 v191, v[84:87] offset:18432
	v_mfma_f32_32x32x16_bf16 v[36:51], v[214:217], v[230:233], v[36:51]
	s_waitcnt vmcnt(2)
	ds_write_b128 v191, v[88:91] offset:55296
	v_mfma_f32_32x32x16_bf16 v[20:35], v[218:221], v[226:229], v[20:35]
	s_waitcnt vmcnt(1)
	ds_write_b128 v192, v[92:95] offset:18432
	v_mfma_f32_32x32x16_bf16 v[4:19], v[218:221], v[230:233], v[4:19]
	s_waitcnt vmcnt(0)
	ds_write_b128 v192, v[104:107] offset:55296
	s_waitcnt lgkmcnt(0)
	s_barrier
	ds_read_b128 v[202:205], v196
	ds_read_b128 v[206:209], v196 offset:32
	ds_read_b128 v[210:213], v196 offset:4608
	ds_read_b128 v[214:217], v196 offset:4640
	ds_read_b128 v[218:221], v197 offset:36864
	ds_read_b128 v[222:225], v197 offset:36896
	ds_read_b128 v[226:229], v197 offset:41472
	ds_read_b128 v[230:233], v197 offset:41504
	s_waitcnt lgkmcnt(3)
	v_mfma_f32_32x32x16_bf16 v[52:67], v[202:205], v[218:221], v[52:67]
	s_waitcnt lgkmcnt(1)
	v_mfma_f32_32x32x16_bf16 v[36:51], v[202:205], v[226:229], v[36:51]
	v_mfma_f32_32x32x16_bf16 v[4:19], v[210:213], v[226:229], v[4:19]
	s_waitcnt lgkmcnt(0)
	v_mfma_f32_32x32x16_bf16 v[36:51], v[206:209], v[230:233], v[36:51]
	v_mfma_f32_32x32x16_bf16 v[4:19], v[214:217], v[230:233], v[4:19]
	ds_read_b128 v[230:233], v197 offset:41568
	ds_read_b128 v[202:205], v196 offset:4672
	v_mfma_f32_32x32x16_bf16 v[20:35], v[210:213], v[218:221], v[20:35]
	ds_read_b128 v[218:221], v196 offset:4704
	ds_read_b128 v[210:213], v196 offset:64
	v_mfma_f32_32x32x16_bf16 v[52:67], v[206:209], v[222:225], v[52:67]
	ds_read_b128 v[226:229], v197 offset:36960
	ds_read_b128 v[206:209], v197 offset:41536
	v_mfma_f32_32x32x16_bf16 v[20:35], v[214:217], v[222:225], v[20:35]
	ds_read_b128 v[222:225], v197 offset:36928
	ds_read_b128 v[214:217], v196 offset:96
	s_waitcnt lgkmcnt(1)
	v_mfma_f32_32x32x16_bf16 v[52:67], v[210:213], v[222:225], v[52:67]
	v_mfma_f32_32x32x16_bf16 v[36:51], v[210:213], v[206:209], v[36:51]
	v_mfma_f32_32x32x16_bf16 v[20:35], v[202:205], v[222:225], v[20:35]
	v_mfma_f32_32x32x16_bf16 v[4:19], v[202:205], v[206:209], v[4:19]
	s_waitcnt lgkmcnt(0)
	v_mfma_f32_32x32x16_bf16 v[52:67], v[214:217], v[226:229], v[52:67]
	v_mfma_f32_32x32x16_bf16 v[36:51], v[214:217], v[230:233], v[36:51]
	v_mfma_f32_32x32x16_bf16 v[20:35], v[218:221], v[226:229], v[20:35]
	v_mfma_f32_32x32x16_bf16 v[4:19], v[218:221], v[230:233], v[4:19]
	s_waitcnt lgkmcnt(0)
	s_barrier
	s_nop 7
	s_nop 3
	s_branch .LBB0_1555

; __global__ void __launch_bounds__(NTHREADS, 2) mega_fwd(Params p, int ph_lo, int ph_hi) {
;     extern __shared__ __align__(16) unsigned char smem[];
	.amdhsa_kernel _Z8mega_fwd6Paramsii
		.amdhsa_group_segment_fixed_size 0
		.amdhsa_private_segment_fixed_size 0
		.amdhsa_kernarg_size 552
		.amdhsa_user_sgpr_count 2
		.amdhsa_user_sgpr_dispatch_ptr 0
		.amdhsa_user_sgpr_queue_ptr 0
		.amdhsa_user_sgpr_kernarg_segment_ptr 1
		.amdhsa_user_sgpr_dispatch_id 0
		.amdhsa_user_sgpr_kernarg_preload_length 0
		.amdhsa_user_sgpr_kernarg_preload_offset 0
		.amdhsa_user_sgpr_private_segment_size 0
		.amdhsa_uses_dynamic_stack 0
		.amdhsa_enable_private_segment 0
		.amdhsa_system_sgpr_workgroup_id_x 1
		.amdhsa_system_sgpr_workgroup_id_y 0
		.amdhsa_system_sgpr_workgroup_id_z 0
		.amdhsa_system_sgpr_workgroup_info 0
		.amdhsa_system_vgpr_workitem_id 2
		.amdhsa_next_free_vgpr 256
		.amdhsa_next_free_sgpr 102
		.amdhsa_accum_offset 256
		.amdhsa_reserve_vcc 1
		.amdhsa_float_round_mode_32 0
		.amdhsa_float_round_mode_16_64 0
		.amdhsa_float_denorm_mode_32 3
		.amdhsa_float_denorm_mode_16_64 3
		.amdhsa_dx10_clamp 1
		.amdhsa_ieee_mode 1
		.amdhsa_fp16_overflow 0
		.amdhsa_tg_split 0
		.amdhsa_exception_fp_ieee_invalid_op 0
		.amdhsa_exception_fp_denorm_src 0
		.amdhsa_exception_fp_ieee_div_zero 0
		.amdhsa_exception_fp_ieee_overflow 0
		.amdhsa_exception_fp_ieee_underflow 0
		.amdhsa_exception_fp_ieee_inexact 0
		.amdhsa_exception_int_div_zero 0
	.end_amdhsa_kernel

; __global__ void __launch_bounds__(NTHREADS, 2) mega_fwd(Params p, int ph_lo, int ph_hi) {
;     extern __shared__ __align__(16) unsigned char smem[];
amdhsa.kernels:
  - .agpr_count:     0
    .args:
      - .offset:         0
        .size:           288
        .value_kind:     by_value
      - .offset:         288
        .size:           4
        .value_kind:     by_value
      - .offset:         292
        .size:           4
        .value_kind:     by_value
      - .offset:         296
        .size:           4
        .value_kind:     hidden_block_count_x
      - .offset:         300
        .size:           4
        .value_kind:     hidden_block_count_y
      - .offset:         304
        .size:           4
        .value_kind:     hidden_block_count_z
      - .offset:         308
        .size:           2
        .value_kind:     hidden_group_size_x
      - .offset:         310
        .size:           2
        .value_kind:     hidden_group_size_y
      - .offset:         312
        .size:           2
        .value_kind:     hidden_group_size_z
      - .offset:         314
        .size:           2
        .value_kind:     hidden_remainder_x
      - .offset:         316
        .size:           2
        .value_kind:     hidden_remainder_y
      - .offset:         318
        .size:           2
        .value_kind:     hidden_remainder_z
      - .offset:         336
        .size:           8
        .value_kind:     hidden_global_offset_x
      - .offset:         344
        .size:           8
        .value_kind:     hidden_global_offset_y
      - .offset:         352
        .size:           8
        .value_kind:     hidden_global_offset_z
      - .offset:         360
        .size:           2
        .value_kind:     hidden_grid_dims
      - .offset:         384
        .size:           8
        .value_kind:     hidden_multigrid_sync_arg
      - .offset:         416
        .size:           4
        .value_kind:     hidden_dynamic_lds_size
    .group_segment_fixed_size: 0
    .kernarg_segment_align: 8
    .kernarg_segment_size: 552
    .language:       OpenCL C
    .language_version:
      - 2
      - 0
    .max_flat_workgroup_size: 256
    .name:           _Z8mega_fwd6Paramsii
    .private_segment_fixed_size: 0
    .sgpr_count:     108
    .sgpr_spill_count: 251
    .symbol:         _Z8mega_fwd6Paramsii.kd
    .uniform_work_group_size: 1
    .uses_dynamic_stack: false
    .vgpr_count:     256
    .vgpr_spill_count: 0
    .wavefront_size: 64
